# SG unit epilogue: 64 serialised gate loads (global_load_ushort + full vmcnt wait each) and 8 bias loads hoisted into one batch before use
# speedup vs baseline: 1.0220x; 1.0170x over previous
; __device__ __forceinline__ int opaque_tid() { int t; asm volatile("v_mov_b32 %0, %1" : "=v"(t) : "v"((int)threadIdx.x)); return t; }
; #define ws (opq(P.ws))
; __device__ __forceinline__ void sg_unit(const Params& P, int l, int chunk, char* shm, float* ssb) {
;     const int tid_ = opaque_tid(), lane = tid_ & 63, wid = __builtin_amdgcn_readfirstlane(tid_ >> 6);
;     unsigned char* ws = P.ws;
;     const bf16_t* qkv = (const bf16_t*)(ws + WS_QKV); bf16_t* omix = (bf16_t*)(ws + WS_OMIX);
;     const bf16_t* Wsb = (const bf16_t*)(ws + WS_WS) + (size_t)l * 4 * 128 * 128;
;     const int R0 = chunk * 128;
;     bf16_t* vt = (bf16_t*)(shm + SG_VT);
;     const float* gs = P.g_sgu + l * 256;
;     const f32x4 g4 = *(const f32x4*)(gs + 4 * lane);
;     for (int q = wid * 16; q < wid * 16 + 16; ++q) {
;         const u32x2 vv = *(const u32x2*)(qkv + (size_t)(R0 + q) * DIN + C_V + 4 * lane);
;         f32x4 v; v[0] = __uint_as_float(vv.x << 16); v[1] = __uint_as_float(vv.x & 0xffff0000u); v[2] = __uint_as_float(vv.y << 16); v[3] = __uint_as_float(vv.y & 0xffff0000u);
.LBB0_556:
	s_andn2_b64 vcc, exec, s[0:1]
	s_cbranch_vccnz .LBB0_579
	s_add_i32 s3, s48, 0xfffffd00
	s_add_i32 s0, s48, 0xfffffcbe
	s_cmpk_lt_u32 s3, 0x42
	s_cselect_b32 s0, s3, s0
	s_cmp_lt_u32 s0, 64
	v_readlane_b32 s4, v252, 11
	s_cselect_b64 s[0:1], -1, 0
	v_readlane_b32 s5, v252, 12
	s_or_b64 s[0:1], s[4:5], s[0:1]
	s_andn2_b64 vcc, exec, s[0:1]
	s_cbranch_vccnz .LBB0_579
	s_mov_b64 s[4:5], s[76:77]
	v_mov_b32 v12, v214
	v_readlane_b32 s0, v252, 18
	v_and_b32_e32 v13, 63, v12
	v_lshlrev_b32_e32 v0, 4, v13
	v_readlane_b32 s1, v252, 19
	v_xor_b32_e32 v6, 1, v220
	v_readfirstlane_b32 s6, v12
	s_ashr_i32 s2, s6, 6
	v_readlane_b32 s8, v254, 36
	s_mov_b32 s7, 0
	global_load_dwordx4 v[2:5], v0, s[0:1]
	v_and_b32_e32 v0, 64, v220
	v_add_u32_e32 v0, 64, v0
	v_cmp_lt_i32_e32 vcc, v6, v0
	s_lshl_b32 s1, s2, 5
	s_add_i32 s1, s1, 0
	v_cndmask_b32_e32 v6, v220, v6, vcc
	v_lshlrev_b32_e32 v17, 2, v6
	v_xor_b32_e32 v6, 2, v220
	v_cmp_lt_i32_e32 vcc, v6, v0
	s_lshl_b32 s0, s2, 4
	s_nop 0
	v_cndmask_b32_e32 v6, v220, v6, vcc
	v_lshlrev_b32_e32 v83, 2, v6
	v_xor_b32_e32 v6, 4, v220
	v_cmp_lt_i32_e32 vcc, v6, v0
	s_nop 1
	v_cndmask_b32_e32 v6, v220, v6, vcc
	v_lshlrev_b32_e32 v82, 2, v6
	v_xor_b32_e32 v6, 8, v220
	v_cmp_lt_i32_e32 vcc, v6, v0
	s_nop 1
	v_cndmask_b32_e32 v6, v220, v6, vcc
	v_lshlrev_b32_e32 v14, 2, v6
	v_xor_b32_e32 v6, 16, v220
	v_cmp_lt_i32_e32 vcc, v6, v0
	s_nop 1
	v_cndmask_b32_e32 v6, v220, v6, vcc
	v_lshlrev_b32_e32 v15, 2, v6
	v_xor_b32_e32 v6, 32, v220
	v_cmp_lt_i32_e32 vcc, v6, v0
	s_nop 1
	v_cndmask_b32_e32 v0, v220, v6, vcc
	v_lshlrev_b32_e32 v18, 2, v0
	v_mov_b32_e32 v0, s1
	s_movk_i32 s1, 0x440
	v_mad_u32_u24 v19, v13, s1, v0
	s_lshl_b32 s1, s48, 7
	s_add_i32 s0, s1, s0
	s_add_i32 s0, s0, 0xfffe8000
	s_mul_hi_i32 s1, s0, 0x1200
	s_mulk_i32 s0, 0x1200
	s_add_u32 s0, s8, s0
	v_readlane_b32 s8, v254, 37
	v_lshlrev_b32_e32 v0, 3, v13
	s_addc_u32 s1, s8, s1
	v_lshl_add_u64 v[6:7], s[0:1], 0, v[0:1]
	s_mov_b64 s[8:9], 0x1200
	global_load_dwordx2 v[96:97], v[6:7], off
	v_lshl_add_u64 v[6:7], v[6:7], 0, s[8:9]
	global_load_dwordx2 v[98:99], v[6:7], off
	v_lshl_add_u64 v[6:7], v[6:7], 0, s[8:9]
	global_load_dwordx2 v[100:101], v[6:7], off
	v_lshl_add_u64 v[6:7], v[6:7], 0, s[8:9]
	global_load_dwordx2 v[102:103], v[6:7], off
	v_lshl_add_u64 v[6:7], v[6:7], 0, s[8:9]
	global_load_dwordx2 v[104:105], v[6:7], off
	v_lshl_add_u64 v[6:7], v[6:7], 0, s[8:9]
	global_load_dwordx2 v[106:107], v[6:7], off
	v_lshl_add_u64 v[6:7], v[6:7], 0, s[8:9]
	global_load_dwordx2 v[108:109], v[6:7], off
	v_lshl_add_u64 v[6:7], v[6:7], 0, s[8:9]
	global_load_dwordx2 v[110:111], v[6:7], off
	v_lshl_add_u64 v[6:7], v[6:7], 0, s[8:9]
	global_load_dwordx2 v[112:113], v[6:7], off
	v_lshl_add_u64 v[6:7], v[6:7], 0, s[8:9]
	global_load_dwordx2 v[114:115], v[6:7], off
	v_lshl_add_u64 v[6:7], v[6:7], 0, s[8:9]
	global_load_dwordx2 v[116:117], v[6:7], off
	v_lshl_add_u64 v[6:7], v[6:7], 0, s[8:9]
	global_load_dwordx2 v[118:119], v[6:7], off
	v_lshl_add_u64 v[6:7], v[6:7], 0, s[8:9]
	global_load_dwordx2 v[120:121], v[6:7], off
	v_lshl_add_u64 v[6:7], v[6:7], 0, s[8:9]
	global_load_dwordx2 v[122:123], v[6:7], off
	v_lshl_add_u64 v[6:7], v[6:7], 0, s[8:9]
	global_load_dwordx2 v[124:125], v[6:7], off
	v_lshl_add_u64 v[6:7], v[6:7], 0, s[8:9]
	global_load_dwordx2 v[126:127], v[6:7], off
	s_waitcnt vmcnt(0)
	v_lshlrev_b32_e32 v130, 16, v97
	v_lshlrev_b32_e32 v128, 16, v96
	v_and_b32_e32 v131, 0xffff0000, v97
	v_and_b32_e32 v129, 0xffff0000, v96
	v_lshlrev_b32_e32 v134, 16, v99
	v_lshlrev_b32_e32 v132, 16, v98
	v_and_b32_e32 v135, 0xffff0000, v99
	v_and_b32_e32 v133, 0xffff0000, v98
	v_lshlrev_b32_e32 v138, 16, v101
	v_lshlrev_b32_e32 v136, 16, v100
	v_and_b32_e32 v139, 0xffff0000, v101
	v_and_b32_e32 v137, 0xffff0000, v100
	v_lshlrev_b32_e32 v142, 16, v103
	v_lshlrev_b32_e32 v140, 16, v102
	v_and_b32_e32 v143, 0xffff0000, v103
	v_and_b32_e32 v141, 0xffff0000, v102
	v_lshlrev_b32_e32 v146, 16, v105
	v_lshlrev_b32_e32 v144, 16, v104
	v_and_b32_e32 v147, 0xffff0000, v105
	v_and_b32_e32 v145, 0xffff0000, v104
	v_lshlrev_b32_e32 v150, 16, v107
	v_lshlrev_b32_e32 v148, 16, v106
	v_and_b32_e32 v151, 0xffff0000, v107
	v_and_b32_e32 v149, 0xffff0000, v106
	v_lshlrev_b32_e32 v154, 16, v109
	v_lshlrev_b32_e32 v152, 16, v108
	v_and_b32_e32 v155, 0xffff0000, v109
	v_and_b32_e32 v153, 0xffff0000, v108
	v_lshlrev_b32_e32 v158, 16, v111
	v_lshlrev_b32_e32 v156, 16, v110
	v_and_b32_e32 v159, 0xffff0000, v111
	v_and_b32_e32 v157, 0xffff0000, v110
	v_lshlrev_b32_e32 v162, 16, v113
	v_lshlrev_b32_e32 v160, 16, v112
	v_and_b32_e32 v163, 0xffff0000, v113
	v_and_b32_e32 v161, 0xffff0000, v112
	v_lshlrev_b32_e32 v166, 16, v115
	v_lshlrev_b32_e32 v164, 16, v114
	v_and_b32_e32 v167, 0xffff0000, v115
	v_and_b32_e32 v165, 0xffff0000, v114
	v_lshlrev_b32_e32 v170, 16, v117
	v_lshlrev_b32_e32 v168, 16, v116
	v_and_b32_e32 v171, 0xffff0000, v117
	v_and_b32_e32 v169, 0xffff0000, v116
	v_lshlrev_b32_e32 v174, 16, v119
	v_lshlrev_b32_e32 v172, 16, v118
	v_and_b32_e32 v175, 0xffff0000, v119
	v_and_b32_e32 v173, 0xffff0000, v118
	v_lshlrev_b32_e32 v178, 16, v121
	v_lshlrev_b32_e32 v176, 16, v120
	v_and_b32_e32 v179, 0xffff0000, v121
	v_and_b32_e32 v177, 0xffff0000, v120
	v_lshlrev_b32_e32 v182, 16, v123
	v_lshlrev_b32_e32 v180, 16, v122
	v_and_b32_e32 v183, 0xffff0000, v123
	v_and_b32_e32 v181, 0xffff0000, v122
	v_lshlrev_b32_e32 v186, 16, v125
	v_lshlrev_b32_e32 v184, 16, v124
	v_and_b32_e32 v187, 0xffff0000, v125
	v_and_b32_e32 v185, 0xffff0000, v124
	v_lshlrev_b32_e32 v190, 16, v127
	v_lshlrev_b32_e32 v188, 16, v126
	v_and_b32_e32 v191, 0xffff0000, v127
	v_and_b32_e32 v189, 0xffff0000, v126
; __device__ __forceinline__ float wave_sum(float v) {
; #pragma unroll
;     for (int o = 1; o < 64; o <<= 1) v += __shfl_xor(v, o);
;     return v;
; __device__ __forceinline__ void sg_unit(const Params& P, int l, int chunk, char* shm, float* ssb) {
;     ...
;         const float mean = wave_sum((v[0] + v[1]) + (v[2] + v[3])) * (1.f / 256.f);
	v_add_f32_e32 v208, v128, v129
	v_add_f32_e32 v209, v130, v131
	v_add_f32_e32 v192, v208, v209
	v_add_f32_e32 v208, v132, v133
	v_add_f32_e32 v209, v134, v135
	v_add_f32_e32 v193, v208, v209
	v_add_f32_e32 v208, v136, v137
	v_add_f32_e32 v209, v138, v139
	v_add_f32_e32 v194, v208, v209
	v_add_f32_e32 v208, v140, v141
	v_add_f32_e32 v209, v142, v143
	v_add_f32_e32 v195, v208, v209
	v_add_f32_e32 v208, v144, v145
	v_add_f32_e32 v209, v146, v147
	v_add_f32_e32 v196, v208, v209
	v_add_f32_e32 v208, v148, v149
	v_add_f32_e32 v209, v150, v151
	v_add_f32_e32 v197, v208, v209
	v_add_f32_e32 v208, v152, v153
	v_add_f32_e32 v209, v154, v155
	v_add_f32_e32 v198, v208, v209
	v_add_f32_e32 v208, v156, v157
	v_add_f32_e32 v209, v158, v159
	v_add_f32_e32 v199, v208, v209
	v_add_f32_e32 v208, v160, v161
	v_add_f32_e32 v209, v162, v163
	v_add_f32_e32 v200, v208, v209
	v_add_f32_e32 v208, v164, v165
	v_add_f32_e32 v209, v166, v167
	v_add_f32_e32 v201, v208, v209
	v_add_f32_e32 v208, v168, v169
	v_add_f32_e32 v209, v170, v171
	v_add_f32_e32 v202, v208, v209
	v_add_f32_e32 v208, v172, v173
	v_add_f32_e32 v209, v174, v175
	v_add_f32_e32 v203, v208, v209
	v_add_f32_e32 v208, v176, v177
	v_add_f32_e32 v209, v178, v179
	v_add_f32_e32 v204, v208, v209
	v_add_f32_e32 v208, v180, v181
	v_add_f32_e32 v209, v182, v183
	v_add_f32_e32 v205, v208, v209
	v_add_f32_e32 v208, v184, v185
	v_add_f32_e32 v209, v186, v187
	v_add_f32_e32 v206, v208, v209
	v_add_f32_e32 v208, v188, v189
	v_add_f32_e32 v209, v190, v191
	v_add_f32_e32 v207, v208, v209
	ds_bpermute_b32 v96, v17, v192
	ds_bpermute_b32 v97, v17, v193
	ds_bpermute_b32 v98, v17, v194
	ds_bpermute_b32 v99, v17, v195
	ds_bpermute_b32 v100, v17, v196
	ds_bpermute_b32 v101, v17, v197
	ds_bpermute_b32 v102, v17, v198
	ds_bpermute_b32 v103, v17, v199
	ds_bpermute_b32 v104, v17, v200
	ds_bpermute_b32 v105, v17, v201
	ds_bpermute_b32 v106, v17, v202
	ds_bpermute_b32 v107, v17, v203
	ds_bpermute_b32 v108, v17, v204
	ds_bpermute_b32 v109, v17, v205
	ds_bpermute_b32 v110, v17, v206
	ds_bpermute_b32 v111, v17, v207
	s_waitcnt lgkmcnt(8)
	v_add_f32_e32 v192, v192, v96
	v_add_f32_e32 v193, v193, v97
	v_add_f32_e32 v194, v194, v98
	v_add_f32_e32 v195, v195, v99
	v_add_f32_e32 v196, v196, v100
	v_add_f32_e32 v197, v197, v101
	v_add_f32_e32 v198, v198, v102
	v_add_f32_e32 v199, v199, v103
	s_waitcnt lgkmcnt(0)
	v_add_f32_e32 v200, v200, v104
	v_add_f32_e32 v201, v201, v105
	v_add_f32_e32 v202, v202, v106
	v_add_f32_e32 v203, v203, v107
	v_add_f32_e32 v204, v204, v108
	v_add_f32_e32 v205, v205, v109
	v_add_f32_e32 v206, v206, v110
	v_add_f32_e32 v207, v207, v111
	ds_bpermute_b32 v96, v83, v192
	ds_bpermute_b32 v97, v83, v193
	ds_bpermute_b32 v98, v83, v194
	ds_bpermute_b32 v99, v83, v195
	ds_bpermute_b32 v100, v83, v196
	ds_bpermute_b32 v101, v83, v197
	ds_bpermute_b32 v102, v83, v198
	ds_bpermute_b32 v103, v83, v199
	ds_bpermute_b32 v104, v83, v200
	ds_bpermute_b32 v105, v83, v201
	ds_bpermute_b32 v106, v83, v202
	ds_bpermute_b32 v107, v83, v203
	ds_bpermute_b32 v108, v83, v204
	ds_bpermute_b32 v109, v83, v205
	ds_bpermute_b32 v110, v83, v206
	ds_bpermute_b32 v111, v83, v207
	s_waitcnt lgkmcnt(8)
	v_add_f32_e32 v192, v192, v96
	v_add_f32_e32 v193, v193, v97
	v_add_f32_e32 v194, v194, v98
	v_add_f32_e32 v195, v195, v99
	v_add_f32_e32 v196, v196, v100
	v_add_f32_e32 v197, v197, v101
	v_add_f32_e32 v198, v198, v102
	v_add_f32_e32 v199, v199, v103
	s_waitcnt lgkmcnt(0)
	v_add_f32_e32 v200, v200, v104
	v_add_f32_e32 v201, v201, v105
	v_add_f32_e32 v202, v202, v106
	v_add_f32_e32 v203, v203, v107
	v_add_f32_e32 v204, v204, v108
	v_add_f32_e32 v205, v205, v109
	v_add_f32_e32 v206, v206, v110
	v_add_f32_e32 v207, v207, v111
	ds_bpermute_b32 v96, v82, v192
	ds_bpermute_b32 v97, v82, v193
	ds_bpermute_b32 v98, v82, v194
	ds_bpermute_b32 v99, v82, v195
	ds_bpermute_b32 v100, v82, v196
	ds_bpermute_b32 v101, v82, v197
	ds_bpermute_b32 v102, v82, v198
	ds_bpermute_b32 v103, v82, v199
	ds_bpermute_b32 v104, v82, v200
	ds_bpermute_b32 v105, v82, v201
	ds_bpermute_b32 v106, v82, v202
	ds_bpermute_b32 v107, v82, v203
	ds_bpermute_b32 v108, v82, v204
	ds_bpermute_b32 v109, v82, v205
	ds_bpermute_b32 v110, v82, v206
	ds_bpermute_b32 v111, v82, v207
	s_waitcnt lgkmcnt(8)
	v_add_f32_e32 v192, v192, v96
	v_add_f32_e32 v193, v193, v97
	v_add_f32_e32 v194, v194, v98
	v_add_f32_e32 v195, v195, v99
	v_add_f32_e32 v196, v196, v100
	v_add_f32_e32 v197, v197, v101
	v_add_f32_e32 v198, v198, v102
	v_add_f32_e32 v199, v199, v103
	s_waitcnt lgkmcnt(0)
	v_add_f32_e32 v200, v200, v104
	v_add_f32_e32 v201, v201, v105
	v_add_f32_e32 v202, v202, v106
	v_add_f32_e32 v203, v203, v107
	v_add_f32_e32 v204, v204, v108
	v_add_f32_e32 v205, v205, v109
	v_add_f32_e32 v206, v206, v110
	v_add_f32_e32 v207, v207, v111
	ds_bpermute_b32 v96, v14, v192
	ds_bpermute_b32 v97, v14, v193
	ds_bpermute_b32 v98, v14, v194
	ds_bpermute_b32 v99, v14, v195
	ds_bpermute_b32 v100, v14, v196
	ds_bpermute_b32 v101, v14, v197
	ds_bpermute_b32 v102, v14, v198
	ds_bpermute_b32 v103, v14, v199
	ds_bpermute_b32 v104, v14, v200
	ds_bpermute_b32 v105, v14, v201
	ds_bpermute_b32 v106, v14, v202
	ds_bpermute_b32 v107, v14, v203
	ds_bpermute_b32 v108, v14, v204
	ds_bpermute_b32 v109, v14, v205
	ds_bpermute_b32 v110, v14, v206
	ds_bpermute_b32 v111, v14, v207
	s_waitcnt lgkmcnt(8)
	v_add_f32_e32 v192, v192, v96
	v_add_f32_e32 v193, v193, v97
	v_add_f32_e32 v194, v194, v98
	v_add_f32_e32 v195, v195, v99
	v_add_f32_e32 v196, v196, v100
	v_add_f32_e32 v197, v197, v101
	v_add_f32_e32 v198, v198, v102
	v_add_f32_e32 v199, v199, v103
	s_waitcnt lgkmcnt(0)
; __device__ __forceinline__ void sg_unit(const Params& P, int l, int chunk, char* shm, float* ssb) {
;     ...
;         const float mean = wave_sum((v[0] + v[1]) + (v[2] + v[3])) * (1.f / 256.f);
;         v = v - mean; const f32x4 sq = v * v;
;         const float rstd = 1.f / sqrtf(wave_sum((sq[0] + sq[1]) + (sq[2] + sq[3])) * (1.f / 256.f) + LN_EPS);
	v_add_f32_e32 v200, v200, v104
	v_add_f32_e32 v201, v201, v105
	v_add_f32_e32 v202, v202, v106
	v_add_f32_e32 v203, v203, v107
	v_add_f32_e32 v204, v204, v108
	v_add_f32_e32 v205, v205, v109
	v_add_f32_e32 v206, v206, v110
	v_add_f32_e32 v207, v207, v111
	ds_bpermute_b32 v96, v15, v192
	ds_bpermute_b32 v97, v15, v193
	ds_bpermute_b32 v98, v15, v194
	ds_bpermute_b32 v99, v15, v195
	ds_bpermute_b32 v100, v15, v196
	ds_bpermute_b32 v101, v15, v197
	ds_bpermute_b32 v102, v15, v198
	ds_bpermute_b32 v103, v15, v199
	ds_bpermute_b32 v104, v15, v200
	ds_bpermute_b32 v105, v15, v201
	ds_bpermute_b32 v106, v15, v202
	ds_bpermute_b32 v107, v15, v203
	ds_bpermute_b32 v108, v15, v204
	ds_bpermute_b32 v109, v15, v205
	ds_bpermute_b32 v110, v15, v206
	ds_bpermute_b32 v111, v15, v207
	s_waitcnt lgkmcnt(8)
	v_add_f32_e32 v192, v192, v96
	v_add_f32_e32 v193, v193, v97
	v_add_f32_e32 v194, v194, v98
	v_add_f32_e32 v195, v195, v99
	v_add_f32_e32 v196, v196, v100
	v_add_f32_e32 v197, v197, v101
	v_add_f32_e32 v198, v198, v102
	v_add_f32_e32 v199, v199, v103
	s_waitcnt lgkmcnt(0)
	v_add_f32_e32 v200, v200, v104
	v_add_f32_e32 v201, v201, v105
	v_add_f32_e32 v202, v202, v106
	v_add_f32_e32 v203, v203, v107
	v_add_f32_e32 v204, v204, v108
	v_add_f32_e32 v205, v205, v109
	v_add_f32_e32 v206, v206, v110
	v_add_f32_e32 v207, v207, v111
	ds_bpermute_b32 v96, v18, v192
	ds_bpermute_b32 v97, v18, v193
	ds_bpermute_b32 v98, v18, v194
	ds_bpermute_b32 v99, v18, v195
	ds_bpermute_b32 v100, v18, v196
	ds_bpermute_b32 v101, v18, v197
	ds_bpermute_b32 v102, v18, v198
	ds_bpermute_b32 v103, v18, v199
	ds_bpermute_b32 v104, v18, v200
	ds_bpermute_b32 v105, v18, v201
	ds_bpermute_b32 v106, v18, v202
	ds_bpermute_b32 v107, v18, v203
	ds_bpermute_b32 v108, v18, v204
	ds_bpermute_b32 v109, v18, v205
	ds_bpermute_b32 v110, v18, v206
	ds_bpermute_b32 v111, v18, v207
	s_waitcnt lgkmcnt(8)
	v_add_f32_e32 v192, v192, v96
	v_add_f32_e32 v193, v193, v97
	v_add_f32_e32 v194, v194, v98
	v_add_f32_e32 v195, v195, v99
	v_add_f32_e32 v196, v196, v100
	v_add_f32_e32 v197, v197, v101
	v_add_f32_e32 v198, v198, v102
	v_add_f32_e32 v199, v199, v103
	s_waitcnt lgkmcnt(0)
	v_add_f32_e32 v200, v200, v104
	v_add_f32_e32 v201, v201, v105
	v_add_f32_e32 v202, v202, v106
	v_add_f32_e32 v203, v203, v107
	v_add_f32_e32 v204, v204, v108
	v_add_f32_e32 v205, v205, v109
	v_add_f32_e32 v206, v206, v110
	v_add_f32_e32 v207, v207, v111
	v_fmac_f32_e32 v129, 0xbb800000, v192
	v_fmac_f32_e32 v131, 0xbb800000, v192
	v_fmac_f32_e32 v130, 0xbb800000, v192
	v_fmac_f32_e32 v128, 0xbb800000, v192
	v_fmac_f32_e32 v133, 0xbb800000, v193
	v_fmac_f32_e32 v135, 0xbb800000, v193
	v_fmac_f32_e32 v134, 0xbb800000, v193
	v_fmac_f32_e32 v132, 0xbb800000, v193
	v_fmac_f32_e32 v137, 0xbb800000, v194
	v_fmac_f32_e32 v139, 0xbb800000, v194
	v_fmac_f32_e32 v138, 0xbb800000, v194
	v_fmac_f32_e32 v136, 0xbb800000, v194
	v_fmac_f32_e32 v141, 0xbb800000, v195
	v_fmac_f32_e32 v143, 0xbb800000, v195
	v_fmac_f32_e32 v142, 0xbb800000, v195
	v_fmac_f32_e32 v140, 0xbb800000, v195
	v_fmac_f32_e32 v145, 0xbb800000, v196
	v_fmac_f32_e32 v147, 0xbb800000, v196
	v_fmac_f32_e32 v146, 0xbb800000, v196
	v_fmac_f32_e32 v144, 0xbb800000, v196
	v_fmac_f32_e32 v149, 0xbb800000, v197
	v_fmac_f32_e32 v151, 0xbb800000, v197
	v_fmac_f32_e32 v150, 0xbb800000, v197
	v_fmac_f32_e32 v148, 0xbb800000, v197
	v_fmac_f32_e32 v153, 0xbb800000, v198
	v_fmac_f32_e32 v155, 0xbb800000, v198
	v_fmac_f32_e32 v154, 0xbb800000, v198
	v_fmac_f32_e32 v152, 0xbb800000, v198
	v_fmac_f32_e32 v157, 0xbb800000, v199
	v_fmac_f32_e32 v159, 0xbb800000, v199
	v_fmac_f32_e32 v158, 0xbb800000, v199
	v_fmac_f32_e32 v156, 0xbb800000, v199
	v_fmac_f32_e32 v161, 0xbb800000, v200
	v_fmac_f32_e32 v163, 0xbb800000, v200
	v_fmac_f32_e32 v162, 0xbb800000, v200
	v_fmac_f32_e32 v160, 0xbb800000, v200
	v_fmac_f32_e32 v165, 0xbb800000, v201
	v_fmac_f32_e32 v167, 0xbb800000, v201
	v_fmac_f32_e32 v166, 0xbb800000, v201
	v_fmac_f32_e32 v164, 0xbb800000, v201
	v_fmac_f32_e32 v169, 0xbb800000, v202
	v_fmac_f32_e32 v171, 0xbb800000, v202
	v_fmac_f32_e32 v170, 0xbb800000, v202
	v_fmac_f32_e32 v168, 0xbb800000, v202
	v_fmac_f32_e32 v173, 0xbb800000, v203
	v_fmac_f32_e32 v175, 0xbb800000, v203
	v_fmac_f32_e32 v174, 0xbb800000, v203
	v_fmac_f32_e32 v172, 0xbb800000, v203
	v_fmac_f32_e32 v177, 0xbb800000, v204
	v_fmac_f32_e32 v179, 0xbb800000, v204
	v_fmac_f32_e32 v178, 0xbb800000, v204
	v_fmac_f32_e32 v176, 0xbb800000, v204
	v_fmac_f32_e32 v181, 0xbb800000, v205
	v_fmac_f32_e32 v183, 0xbb800000, v205
	v_fmac_f32_e32 v182, 0xbb800000, v205
	v_fmac_f32_e32 v180, 0xbb800000, v205
	v_fmac_f32_e32 v185, 0xbb800000, v206
	v_fmac_f32_e32 v187, 0xbb800000, v206
	v_fmac_f32_e32 v186, 0xbb800000, v206
	v_fmac_f32_e32 v184, 0xbb800000, v206
	v_fmac_f32_e32 v189, 0xbb800000, v207
	v_fmac_f32_e32 v191, 0xbb800000, v207
	v_fmac_f32_e32 v190, 0xbb800000, v207
	v_fmac_f32_e32 v188, 0xbb800000, v207
	v_mul_f32_e32 v208, v128, v128
	v_mul_f32_e32 v209, v129, v129
	v_mul_f32_e32 v210, v130, v130
	v_mul_f32_e32 v211, v131, v131
	v_add_f32_e32 v208, v209, v208
	v_add_f32_e32 v210, v210, v211
	v_add_f32_e32 v192, v208, v210
	v_mul_f32_e32 v208, v132, v132
	v_mul_f32_e32 v209, v133, v133
	v_mul_f32_e32 v210, v134, v134
	v_mul_f32_e32 v211, v135, v135
	v_add_f32_e32 v208, v209, v208
	v_add_f32_e32 v210, v210, v211
	v_add_f32_e32 v193, v208, v210
	v_mul_f32_e32 v208, v136, v136
	v_mul_f32_e32 v209, v137, v137
	v_mul_f32_e32 v210, v138, v138
	v_mul_f32_e32 v211, v139, v139
	v_add_f32_e32 v208, v209, v208
	v_add_f32_e32 v210, v210, v211
	v_add_f32_e32 v194, v208, v210
	v_mul_f32_e32 v208, v140, v140
	v_mul_f32_e32 v209, v141, v141
; __device__ __forceinline__ void sg_unit(const Params& P, int l, int chunk, char* shm, float* ssb) {
;     ...
;         v = v - mean; const f32x4 sq = v * v;
;         const float rstd = 1.f / sqrtf(wave_sum((sq[0] + sq[1]) + (sq[2] + sq[3])) * (1.f / 256.f) + LN_EPS);
	v_mul_f32_e32 v210, v142, v142
	v_mul_f32_e32 v211, v143, v143
	v_add_f32_e32 v208, v209, v208
	v_add_f32_e32 v210, v210, v211
	v_add_f32_e32 v195, v208, v210
	v_mul_f32_e32 v208, v144, v144
	v_mul_f32_e32 v209, v145, v145
	v_mul_f32_e32 v210, v146, v146
	v_mul_f32_e32 v211, v147, v147
	v_add_f32_e32 v208, v209, v208
	v_add_f32_e32 v210, v210, v211
	v_add_f32_e32 v196, v208, v210
	v_mul_f32_e32 v208, v148, v148
	v_mul_f32_e32 v209, v149, v149
	v_mul_f32_e32 v210, v150, v150
	v_mul_f32_e32 v211, v151, v151
	v_add_f32_e32 v208, v209, v208
	v_add_f32_e32 v210, v210, v211
	v_add_f32_e32 v197, v208, v210
	v_mul_f32_e32 v208, v152, v152
	v_mul_f32_e32 v209, v153, v153
	v_mul_f32_e32 v210, v154, v154
	v_mul_f32_e32 v211, v155, v155
	v_add_f32_e32 v208, v209, v208
	v_add_f32_e32 v210, v210, v211
	v_add_f32_e32 v198, v208, v210
	v_mul_f32_e32 v208, v156, v156
	v_mul_f32_e32 v209, v157, v157
	v_mul_f32_e32 v210, v158, v158
	v_mul_f32_e32 v211, v159, v159
	v_add_f32_e32 v208, v209, v208
	v_add_f32_e32 v210, v210, v211
	v_add_f32_e32 v199, v208, v210
	v_mul_f32_e32 v208, v160, v160
	v_mul_f32_e32 v209, v161, v161
	v_mul_f32_e32 v210, v162, v162
	v_mul_f32_e32 v211, v163, v163
	v_add_f32_e32 v208, v209, v208
	v_add_f32_e32 v210, v210, v211
	v_add_f32_e32 v200, v208, v210
	v_mul_f32_e32 v208, v164, v164
	v_mul_f32_e32 v209, v165, v165
	v_mul_f32_e32 v210, v166, v166
	v_mul_f32_e32 v211, v167, v167
	v_add_f32_e32 v208, v209, v208
	v_add_f32_e32 v210, v210, v211
	v_add_f32_e32 v201, v208, v210
	v_mul_f32_e32 v208, v168, v168
	v_mul_f32_e32 v209, v169, v169
	v_mul_f32_e32 v210, v170, v170
	v_mul_f32_e32 v211, v171, v171
	v_add_f32_e32 v208, v209, v208
	v_add_f32_e32 v210, v210, v211
	v_add_f32_e32 v202, v208, v210
	v_mul_f32_e32 v208, v172, v172
	v_mul_f32_e32 v209, v173, v173
	v_mul_f32_e32 v210, v174, v174
	v_mul_f32_e32 v211, v175, v175
	v_add_f32_e32 v208, v209, v208
	v_add_f32_e32 v210, v210, v211
	v_add_f32_e32 v203, v208, v210
	v_mul_f32_e32 v208, v176, v176
	v_mul_f32_e32 v209, v177, v177
	v_mul_f32_e32 v210, v178, v178
	v_mul_f32_e32 v211, v179, v179
	v_add_f32_e32 v208, v209, v208
	v_add_f32_e32 v210, v210, v211
	v_add_f32_e32 v204, v208, v210
	v_mul_f32_e32 v208, v180, v180
	v_mul_f32_e32 v209, v181, v181
	v_mul_f32_e32 v210, v182, v182
	v_mul_f32_e32 v211, v183, v183
	v_add_f32_e32 v208, v209, v208
	v_add_f32_e32 v210, v210, v211
	v_add_f32_e32 v205, v208, v210
	v_mul_f32_e32 v208, v184, v184
	v_mul_f32_e32 v209, v185, v185
	v_mul_f32_e32 v210, v186, v186
	v_mul_f32_e32 v211, v187, v187
	v_add_f32_e32 v208, v209, v208
	v_add_f32_e32 v210, v210, v211
	v_add_f32_e32 v206, v208, v210
	v_mul_f32_e32 v208, v188, v188
	v_mul_f32_e32 v209, v189, v189
	v_mul_f32_e32 v210, v190, v190
	v_mul_f32_e32 v211, v191, v191
	v_add_f32_e32 v208, v209, v208
	v_add_f32_e32 v210, v210, v211
	v_add_f32_e32 v207, v208, v210
	ds_bpermute_b32 v96, v17, v192
	ds_bpermute_b32 v97, v17, v193
	ds_bpermute_b32 v98, v17, v194
	ds_bpermute_b32 v99, v17, v195
	ds_bpermute_b32 v100, v17, v196
	ds_bpermute_b32 v101, v17, v197
	ds_bpermute_b32 v102, v17, v198
	ds_bpermute_b32 v103, v17, v199
	ds_bpermute_b32 v104, v17, v200
	ds_bpermute_b32 v105, v17, v201
	ds_bpermute_b32 v106, v17, v202
	ds_bpermute_b32 v107, v17, v203
	ds_bpermute_b32 v108, v17, v204
	ds_bpermute_b32 v109, v17, v205
	ds_bpermute_b32 v110, v17, v206
	ds_bpermute_b32 v111, v17, v207
	s_waitcnt lgkmcnt(8)
	v_add_f32_e32 v192, v192, v96
	v_add_f32_e32 v193, v193, v97
	v_add_f32_e32 v194, v194, v98
	v_add_f32_e32 v195, v195, v99
	v_add_f32_e32 v196, v196, v100
	v_add_f32_e32 v197, v197, v101
	v_add_f32_e32 v198, v198, v102
	v_add_f32_e32 v199, v199, v103
	s_waitcnt lgkmcnt(0)
	v_add_f32_e32 v200, v200, v104
	v_add_f32_e32 v201, v201, v105
	v_add_f32_e32 v202, v202, v106
	v_add_f32_e32 v203, v203, v107
	v_add_f32_e32 v204, v204, v108
	v_add_f32_e32 v205, v205, v109
	v_add_f32_e32 v206, v206, v110
	v_add_f32_e32 v207, v207, v111
	ds_bpermute_b32 v96, v83, v192
	ds_bpermute_b32 v97, v83, v193
	ds_bpermute_b32 v98, v83, v194
	ds_bpermute_b32 v99, v83, v195
	ds_bpermute_b32 v100, v83, v196
	ds_bpermute_b32 v101, v83, v197
	ds_bpermute_b32 v102, v83, v198
	ds_bpermute_b32 v103, v83, v199
	ds_bpermute_b32 v104, v83, v200
	ds_bpermute_b32 v105, v83, v201
	ds_bpermute_b32 v106, v83, v202
	ds_bpermute_b32 v107, v83, v203
	ds_bpermute_b32 v108, v83, v204
	ds_bpermute_b32 v109, v83, v205
	ds_bpermute_b32 v110, v83, v206
	ds_bpermute_b32 v111, v83, v207
	s_waitcnt lgkmcnt(8)
	v_add_f32_e32 v192, v192, v96
	v_add_f32_e32 v193, v193, v97
	v_add_f32_e32 v194, v194, v98
	v_add_f32_e32 v195, v195, v99
	v_add_f32_e32 v196, v196, v100
	v_add_f32_e32 v197, v197, v101
	v_add_f32_e32 v198, v198, v102
	v_add_f32_e32 v199, v199, v103
	s_waitcnt lgkmcnt(0)
	v_add_f32_e32 v200, v200, v104
	v_add_f32_e32 v201, v201, v105
	v_add_f32_e32 v202, v202, v106
	v_add_f32_e32 v203, v203, v107
	v_add_f32_e32 v204, v204, v108
	v_add_f32_e32 v205, v205, v109
	v_add_f32_e32 v206, v206, v110
	v_add_f32_e32 v207, v207, v111
	ds_bpermute_b32 v96, v82, v192
	ds_bpermute_b32 v97, v82, v193
	ds_bpermute_b32 v98, v82, v194
	ds_bpermute_b32 v99, v82, v195
	ds_bpermute_b32 v100, v82, v196
	ds_bpermute_b32 v101, v82, v197
	ds_bpermute_b32 v102, v82, v198
	ds_bpermute_b32 v103, v82, v199
	ds_bpermute_b32 v104, v82, v200
	ds_bpermute_b32 v105, v82, v201
	ds_bpermute_b32 v106, v82, v202
	ds_bpermute_b32 v107, v82, v203
	ds_bpermute_b32 v108, v82, v204
	ds_bpermute_b32 v109, v82, v205
	ds_bpermute_b32 v110, v82, v206
	ds_bpermute_b32 v111, v82, v207
	s_waitcnt lgkmcnt(8)
; __device__ __forceinline__ unsigned cvtpk_s(float lo, float hi) { typedef __bf16 bf16x2_t __attribute__((ext_vector_type(2))); f32x2 v = {lo, hi}; bf16x2_t b = __builtin_convertvector(v, bf16x2_t); return __builtin_bit_cast(unsigned, b); }
; __device__ __forceinline__ void sg_unit(const Params& P, int l, int chunk, char* shm, float* ssb) {
;     ...
;         const float mean = wave_sum((v[0] + v[1]) + (v[2] + v[3])) * (1.f / 256.f);
;         v = v - mean; const f32x4 sq = v * v;
;         const float rstd = 1.f / sqrtf(wave_sum((sq[0] + sq[1]) + (sq[2] + sq[3])) * (1.f / 256.f) + LN_EPS);
;         v = v * rstd * g4;
; #pragma unroll
;         for (int j = 0; j < 4; ++j) vt[(4 * lane + j) * SG_VT_PITCH + q] = (bf16_t)(at::cvtpk_s(v[j], 0.f) & 0xffffu);
	v_add_f32_e32 v192, v192, v96
	v_add_f32_e32 v193, v193, v97
	v_add_f32_e32 v194, v194, v98
	v_add_f32_e32 v195, v195, v99
	v_add_f32_e32 v196, v196, v100
	v_add_f32_e32 v197, v197, v101
	v_add_f32_e32 v198, v198, v102
	v_add_f32_e32 v199, v199, v103
	s_waitcnt lgkmcnt(0)
	v_add_f32_e32 v200, v200, v104
	v_add_f32_e32 v201, v201, v105
	v_add_f32_e32 v202, v202, v106
	v_add_f32_e32 v203, v203, v107
	v_add_f32_e32 v204, v204, v108
	v_add_f32_e32 v205, v205, v109
	v_add_f32_e32 v206, v206, v110
	v_add_f32_e32 v207, v207, v111
	ds_bpermute_b32 v96, v14, v192
	ds_bpermute_b32 v97, v14, v193
	ds_bpermute_b32 v98, v14, v194
	ds_bpermute_b32 v99, v14, v195
	ds_bpermute_b32 v100, v14, v196
	ds_bpermute_b32 v101, v14, v197
	ds_bpermute_b32 v102, v14, v198
	ds_bpermute_b32 v103, v14, v199
	ds_bpermute_b32 v104, v14, v200
	ds_bpermute_b32 v105, v14, v201
	ds_bpermute_b32 v106, v14, v202
	ds_bpermute_b32 v107, v14, v203
	ds_bpermute_b32 v108, v14, v204
	ds_bpermute_b32 v109, v14, v205
	ds_bpermute_b32 v110, v14, v206
	ds_bpermute_b32 v111, v14, v207
	s_waitcnt lgkmcnt(8)
	v_add_f32_e32 v192, v192, v96
	v_add_f32_e32 v193, v193, v97
	v_add_f32_e32 v194, v194, v98
	v_add_f32_e32 v195, v195, v99
	v_add_f32_e32 v196, v196, v100
	v_add_f32_e32 v197, v197, v101
	v_add_f32_e32 v198, v198, v102
	v_add_f32_e32 v199, v199, v103
	s_waitcnt lgkmcnt(0)
	v_add_f32_e32 v200, v200, v104
	v_add_f32_e32 v201, v201, v105
	v_add_f32_e32 v202, v202, v106
	v_add_f32_e32 v203, v203, v107
	v_add_f32_e32 v204, v204, v108
	v_add_f32_e32 v205, v205, v109
	v_add_f32_e32 v206, v206, v110
	v_add_f32_e32 v207, v207, v111
	ds_bpermute_b32 v96, v15, v192
	ds_bpermute_b32 v97, v15, v193
	ds_bpermute_b32 v98, v15, v194
	ds_bpermute_b32 v99, v15, v195
	ds_bpermute_b32 v100, v15, v196
	ds_bpermute_b32 v101, v15, v197
	ds_bpermute_b32 v102, v15, v198
	ds_bpermute_b32 v103, v15, v199
	ds_bpermute_b32 v104, v15, v200
	ds_bpermute_b32 v105, v15, v201
	ds_bpermute_b32 v106, v15, v202
	ds_bpermute_b32 v107, v15, v203
	ds_bpermute_b32 v108, v15, v204
	ds_bpermute_b32 v109, v15, v205
	ds_bpermute_b32 v110, v15, v206
	ds_bpermute_b32 v111, v15, v207
	s_waitcnt lgkmcnt(8)
	v_add_f32_e32 v192, v192, v96
	v_add_f32_e32 v193, v193, v97
	v_add_f32_e32 v194, v194, v98
	v_add_f32_e32 v195, v195, v99
	v_add_f32_e32 v196, v196, v100
	v_add_f32_e32 v197, v197, v101
	v_add_f32_e32 v198, v198, v102
	v_add_f32_e32 v199, v199, v103
	s_waitcnt lgkmcnt(0)
	v_add_f32_e32 v200, v200, v104
	v_add_f32_e32 v201, v201, v105
	v_add_f32_e32 v202, v202, v106
	v_add_f32_e32 v203, v203, v107
	v_add_f32_e32 v204, v204, v108
	v_add_f32_e32 v205, v205, v109
	v_add_f32_e32 v206, v206, v110
	v_add_f32_e32 v207, v207, v111
	ds_bpermute_b32 v96, v18, v192
	ds_bpermute_b32 v97, v18, v193
	ds_bpermute_b32 v98, v18, v194
	ds_bpermute_b32 v99, v18, v195
	ds_bpermute_b32 v100, v18, v196
	ds_bpermute_b32 v101, v18, v197
	ds_bpermute_b32 v102, v18, v198
	ds_bpermute_b32 v103, v18, v199
	ds_bpermute_b32 v104, v18, v200
	ds_bpermute_b32 v105, v18, v201
	ds_bpermute_b32 v106, v18, v202
	ds_bpermute_b32 v107, v18, v203
	ds_bpermute_b32 v108, v18, v204
	ds_bpermute_b32 v109, v18, v205
	ds_bpermute_b32 v110, v18, v206
	ds_bpermute_b32 v111, v18, v207
	s_waitcnt lgkmcnt(8)
	v_add_f32_e32 v192, v192, v96
	v_add_f32_e32 v193, v193, v97
	v_add_f32_e32 v194, v194, v98
	v_add_f32_e32 v195, v195, v99
	v_add_f32_e32 v196, v196, v100
	v_add_f32_e32 v197, v197, v101
	v_add_f32_e32 v198, v198, v102
	v_add_f32_e32 v199, v199, v103
	s_waitcnt lgkmcnt(0)
	v_add_f32_e32 v200, v200, v104
	v_add_f32_e32 v201, v201, v105
	v_add_f32_e32 v202, v202, v106
	v_add_f32_e32 v203, v203, v107
	v_add_f32_e32 v204, v204, v108
	v_add_f32_e32 v205, v205, v109
	v_add_f32_e32 v206, v206, v110
	v_add_f32_e32 v207, v207, v111
	v_fmamk_f32 v192, v192, 0x3b800000, v216
	v_cmp_gt_f32_e32 vcc, s69, v192
	v_mul_f32_e32 v96, 0x4f800000, v192
	s_nop 0
	v_cndmask_b32_e32 v192, v192, v96, vcc
	v_sqrt_f32_e32 v96, v192
	s_nop 0
	v_add_u32_e32 v97, -1, v96
	v_fma_f32 v98, -v97, v96, v192
	v_cmp_ge_f32_e64 s[0:1], 0, v98
	v_add_u32_e32 v98, 1, v96
	s_nop 0
	v_cndmask_b32_e64 v97, v96, v97, s[0:1]
	v_fma_f32 v96, -v98, v96, v192
	v_cmp_lt_f32_e64 s[0:1], 0, v96
	s_nop 1
	v_cndmask_b32_e64 v96, v97, v98, s[0:1]
	v_mul_f32_e32 v97, 0x37800000, v96
	v_cndmask_b32_e32 v96, v96, v97, vcc
	v_cmp_class_f32_e32 vcc, v192, v217
	s_nop 1
	v_cndmask_b32_e32 v192, v96, v192, vcc
	v_div_scale_f32 v96, s[0:1], v192, v192, 1.0
	v_rcp_f32_e32 v97, v96
	s_nop 0
	v_fma_f32 v98, -v96, v97, 1.0
	v_fmac_f32_e32 v97, v98, v97
	v_div_scale_f32 v98, vcc, 1.0, v192, 1.0
	v_mul_f32_e32 v99, v98, v97
	v_fma_f32 v100, -v96, v99, v98
	v_fmac_f32_e32 v99, v100, v97
	v_fma_f32 v96, -v96, v99, v98
	v_div_fmas_f32 v96, v96, v97, v99
	v_div_fixup_f32 v192, v96, v192, 1.0
	v_mul_f32_e32 v128, v128, v192
	v_mul_f32_e32 v129, v129, v192
	v_mul_f32_e32 v130, v130, v192
	v_mul_f32_e32 v131, v131, v192
	v_mul_f32_e32 v96, v2, v128
	v_cvt_pk_bf16_f32 v96, v96, s0
	v_mul_f32_e32 v97, v3, v129
	v_cvt_pk_bf16_f32 v97, v97, s0
	v_mul_f32_e32 v98, v4, v130
	v_cvt_pk_bf16_f32 v98, v98, s0
	v_mul_f32_e32 v99, v5, v131
	v_cvt_pk_bf16_f32 v99, v99, s0
	ds_write_b16 v19, v96 offset:0
	ds_write_b16 v19, v97 offset:272
	ds_write_b16 v19, v98 offset:544
	ds_write_b16 v19, v99 offset:816
	v_fmamk_f32 v193, v193, 0x3b800000, v216
	v_cmp_gt_f32_e32 vcc, s69, v193
	v_mul_f32_e32 v96, 0x4f800000, v193
	s_nop 0
	v_cndmask_b32_e32 v193, v193, v96, vcc
	v_sqrt_f32_e32 v96, v193
	s_nop 0
	v_add_u32_e32 v97, -1, v96
	v_fma_f32 v98, -v97, v96, v193
	v_cmp_ge_f32_e64 s[0:1], 0, v98
	v_add_u32_e32 v98, 1, v96
	s_nop 0
	v_cndmask_b32_e64 v97, v96, v97, s[0:1]
; __device__ __forceinline__ unsigned cvtpk_s(float lo, float hi) { typedef __bf16 bf16x2_t __attribute__((ext_vector_type(2))); f32x2 v = {lo, hi}; bf16x2_t b = __builtin_convertvector(v, bf16x2_t); return __builtin_bit_cast(unsigned, b); }
; __device__ __forceinline__ void sg_unit(const Params& P, int l, int chunk, char* shm, float* ssb) {
;     ...
;         const float rstd = 1.f / sqrtf(wave_sum((sq[0] + sq[1]) + (sq[2] + sq[3])) * (1.f / 256.f) + LN_EPS);
;         v = v * rstd * g4;
; #pragma unroll
;         for (int j = 0; j < 4; ++j) vt[(4 * lane + j) * SG_VT_PITCH + q] = (bf16_t)(at::cvtpk_s(v[j], 0.f) & 0xffffu);
	v_fma_f32 v96, -v98, v96, v193
	v_cmp_lt_f32_e64 s[0:1], 0, v96
	s_nop 1
	v_cndmask_b32_e64 v96, v97, v98, s[0:1]
	v_mul_f32_e32 v97, 0x37800000, v96
	v_cndmask_b32_e32 v96, v96, v97, vcc
	v_cmp_class_f32_e32 vcc, v193, v217
	s_nop 1
	v_cndmask_b32_e32 v193, v96, v193, vcc
	v_div_scale_f32 v96, s[0:1], v193, v193, 1.0
	v_rcp_f32_e32 v97, v96
	s_nop 0
	v_fma_f32 v98, -v96, v97, 1.0
	v_fmac_f32_e32 v97, v98, v97
	v_div_scale_f32 v98, vcc, 1.0, v193, 1.0
	v_mul_f32_e32 v99, v98, v97
	v_fma_f32 v100, -v96, v99, v98
	v_fmac_f32_e32 v99, v100, v97
	v_fma_f32 v96, -v96, v99, v98
	v_div_fmas_f32 v96, v96, v97, v99
	v_div_fixup_f32 v193, v96, v193, 1.0
	v_mul_f32_e32 v132, v132, v193
	v_mul_f32_e32 v133, v133, v193
	v_mul_f32_e32 v134, v134, v193
	v_mul_f32_e32 v135, v135, v193
	v_mul_f32_e32 v96, v2, v132
	v_cvt_pk_bf16_f32 v96, v96, s0
	v_mul_f32_e32 v97, v3, v133
	v_cvt_pk_bf16_f32 v97, v97, s0
	v_mul_f32_e32 v98, v4, v134
	v_cvt_pk_bf16_f32 v98, v98, s0
	v_mul_f32_e32 v99, v5, v135
	v_cvt_pk_bf16_f32 v99, v99, s0
	ds_write_b16 v19, v96 offset:2
	ds_write_b16 v19, v97 offset:274
	ds_write_b16 v19, v98 offset:546
	ds_write_b16 v19, v99 offset:818
	v_fmamk_f32 v194, v194, 0x3b800000, v216
	v_cmp_gt_f32_e32 vcc, s69, v194
	v_mul_f32_e32 v96, 0x4f800000, v194
	s_nop 0
	v_cndmask_b32_e32 v194, v194, v96, vcc
	v_sqrt_f32_e32 v96, v194
	s_nop 0
	v_add_u32_e32 v97, -1, v96
	v_fma_f32 v98, -v97, v96, v194
	v_cmp_ge_f32_e64 s[0:1], 0, v98
	v_add_u32_e32 v98, 1, v96
	s_nop 0
	v_cndmask_b32_e64 v97, v96, v97, s[0:1]
	v_fma_f32 v96, -v98, v96, v194
	v_cmp_lt_f32_e64 s[0:1], 0, v96
	s_nop 1
	v_cndmask_b32_e64 v96, v97, v98, s[0:1]
	v_mul_f32_e32 v97, 0x37800000, v96
	v_cndmask_b32_e32 v96, v96, v97, vcc
	v_cmp_class_f32_e32 vcc, v194, v217
	s_nop 1
	v_cndmask_b32_e32 v194, v96, v194, vcc
	v_div_scale_f32 v96, s[0:1], v194, v194, 1.0
	v_rcp_f32_e32 v97, v96
	s_nop 0
	v_fma_f32 v98, -v96, v97, 1.0
	v_fmac_f32_e32 v97, v98, v97
	v_div_scale_f32 v98, vcc, 1.0, v194, 1.0
	v_mul_f32_e32 v99, v98, v97
	v_fma_f32 v100, -v96, v99, v98
	v_fmac_f32_e32 v99, v100, v97
	v_fma_f32 v96, -v96, v99, v98
	v_div_fmas_f32 v96, v96, v97, v99
	v_div_fixup_f32 v194, v96, v194, 1.0
	v_mul_f32_e32 v136, v136, v194
	v_mul_f32_e32 v137, v137, v194
	v_mul_f32_e32 v138, v138, v194
	v_mul_f32_e32 v139, v139, v194
	v_mul_f32_e32 v96, v2, v136
	v_cvt_pk_bf16_f32 v96, v96, s0
	v_mul_f32_e32 v97, v3, v137
	v_cvt_pk_bf16_f32 v97, v97, s0
	v_mul_f32_e32 v98, v4, v138
	v_cvt_pk_bf16_f32 v98, v98, s0
	v_mul_f32_e32 v99, v5, v139
	v_cvt_pk_bf16_f32 v99, v99, s0
	ds_write_b16 v19, v96 offset:4
	ds_write_b16 v19, v97 offset:276
	ds_write_b16 v19, v98 offset:548
	ds_write_b16 v19, v99 offset:820
	v_fmamk_f32 v195, v195, 0x3b800000, v216
	v_cmp_gt_f32_e32 vcc, s69, v195
	v_mul_f32_e32 v96, 0x4f800000, v195
	s_nop 0
	v_cndmask_b32_e32 v195, v195, v96, vcc
	v_sqrt_f32_e32 v96, v195
	s_nop 0
	v_add_u32_e32 v97, -1, v96
	v_fma_f32 v98, -v97, v96, v195
	v_cmp_ge_f32_e64 s[0:1], 0, v98
	v_add_u32_e32 v98, 1, v96
	s_nop 0
	v_cndmask_b32_e64 v97, v96, v97, s[0:1]
	v_fma_f32 v96, -v98, v96, v195
	v_cmp_lt_f32_e64 s[0:1], 0, v96
	s_nop 1
	v_cndmask_b32_e64 v96, v97, v98, s[0:1]
	v_mul_f32_e32 v97, 0x37800000, v96
	v_cndmask_b32_e32 v96, v96, v97, vcc
	v_cmp_class_f32_e32 vcc, v195, v217
	s_nop 1
	v_cndmask_b32_e32 v195, v96, v195, vcc
	v_div_scale_f32 v96, s[0:1], v195, v195, 1.0
	v_rcp_f32_e32 v97, v96
	s_nop 0
	v_fma_f32 v98, -v96, v97, 1.0
	v_fmac_f32_e32 v97, v98, v97
	v_div_scale_f32 v98, vcc, 1.0, v195, 1.0
	v_mul_f32_e32 v99, v98, v97
	v_fma_f32 v100, -v96, v99, v98
	v_fmac_f32_e32 v99, v100, v97
	v_fma_f32 v96, -v96, v99, v98
	v_div_fmas_f32 v96, v96, v97, v99
	v_div_fixup_f32 v195, v96, v195, 1.0
	v_mul_f32_e32 v140, v140, v195
	v_mul_f32_e32 v141, v141, v195
	v_mul_f32_e32 v142, v142, v195
	v_mul_f32_e32 v143, v143, v195
	v_mul_f32_e32 v96, v2, v140
	v_cvt_pk_bf16_f32 v96, v96, s0
	v_mul_f32_e32 v97, v3, v141
	v_cvt_pk_bf16_f32 v97, v97, s0
	v_mul_f32_e32 v98, v4, v142
	v_cvt_pk_bf16_f32 v98, v98, s0
	v_mul_f32_e32 v99, v5, v143
	v_cvt_pk_bf16_f32 v99, v99, s0
	ds_write_b16 v19, v96 offset:6
	ds_write_b16 v19, v97 offset:278
	ds_write_b16 v19, v98 offset:550
	ds_write_b16 v19, v99 offset:822
	v_fmamk_f32 v196, v196, 0x3b800000, v216
	v_cmp_gt_f32_e32 vcc, s69, v196
	v_mul_f32_e32 v96, 0x4f800000, v196
	s_nop 0
	v_cndmask_b32_e32 v196, v196, v96, vcc
	v_sqrt_f32_e32 v96, v196
	s_nop 0
	v_add_u32_e32 v97, -1, v96
	v_fma_f32 v98, -v97, v96, v196
	v_cmp_ge_f32_e64 s[0:1], 0, v98
	v_add_u32_e32 v98, 1, v96
	s_nop 0
	v_cndmask_b32_e64 v97, v96, v97, s[0:1]
	v_fma_f32 v96, -v98, v96, v196
	v_cmp_lt_f32_e64 s[0:1], 0, v96
	s_nop 1
	v_cndmask_b32_e64 v96, v97, v98, s[0:1]
	v_mul_f32_e32 v97, 0x37800000, v96
	v_cndmask_b32_e32 v96, v96, v97, vcc
	v_cmp_class_f32_e32 vcc, v196, v217
	s_nop 1
	v_cndmask_b32_e32 v196, v96, v196, vcc
	v_div_scale_f32 v96, s[0:1], v196, v196, 1.0
	v_rcp_f32_e32 v97, v96
	s_nop 0
	v_fma_f32 v98, -v96, v97, 1.0
	v_fmac_f32_e32 v97, v98, v97
	v_div_scale_f32 v98, vcc, 1.0, v196, 1.0
	v_mul_f32_e32 v99, v98, v97
	v_fma_f32 v100, -v96, v99, v98
	v_fmac_f32_e32 v99, v100, v97
	v_fma_f32 v96, -v96, v99, v98
	v_div_fmas_f32 v96, v96, v97, v99
	v_div_fixup_f32 v196, v96, v196, 1.0
	v_mul_f32_e32 v144, v144, v196
	v_mul_f32_e32 v145, v145, v196
	v_mul_f32_e32 v146, v146, v196
	v_mul_f32_e32 v147, v147, v196
	v_mul_f32_e32 v96, v2, v144
	v_cvt_pk_bf16_f32 v96, v96, s0
	v_mul_f32_e32 v97, v3, v145
	v_cvt_pk_bf16_f32 v97, v97, s0
	v_mul_f32_e32 v98, v4, v146
	v_cvt_pk_bf16_f32 v98, v98, s0
	v_mul_f32_e32 v99, v5, v147
	v_cvt_pk_bf16_f32 v99, v99, s0
	ds_write_b16 v19, v96 offset:8
; __device__ __forceinline__ unsigned cvtpk_s(float lo, float hi) { typedef __bf16 bf16x2_t __attribute__((ext_vector_type(2))); f32x2 v = {lo, hi}; bf16x2_t b = __builtin_convertvector(v, bf16x2_t); return __builtin_bit_cast(unsigned, b); }
; __device__ __forceinline__ void sg_unit(const Params& P, int l, int chunk, char* shm, float* ssb) {
;     ...
;         const float rstd = 1.f / sqrtf(wave_sum((sq[0] + sq[1]) + (sq[2] + sq[3])) * (1.f / 256.f) + LN_EPS);
;         v = v * rstd * g4;
; #pragma unroll
;         for (int j = 0; j < 4; ++j) vt[(4 * lane + j) * SG_VT_PITCH + q] = (bf16_t)(at::cvtpk_s(v[j], 0.f) & 0xffffu);
	ds_write_b16 v19, v97 offset:280
	ds_write_b16 v19, v98 offset:552
	ds_write_b16 v19, v99 offset:824
	v_fmamk_f32 v197, v197, 0x3b800000, v216
	v_cmp_gt_f32_e32 vcc, s69, v197
	v_mul_f32_e32 v96, 0x4f800000, v197
	s_nop 0
	v_cndmask_b32_e32 v197, v197, v96, vcc
	v_sqrt_f32_e32 v96, v197
	s_nop 0
	v_add_u32_e32 v97, -1, v96
	v_fma_f32 v98, -v97, v96, v197
	v_cmp_ge_f32_e64 s[0:1], 0, v98
	v_add_u32_e32 v98, 1, v96
	s_nop 0
	v_cndmask_b32_e64 v97, v96, v97, s[0:1]
	v_fma_f32 v96, -v98, v96, v197
	v_cmp_lt_f32_e64 s[0:1], 0, v96
	s_nop 1
	v_cndmask_b32_e64 v96, v97, v98, s[0:1]
	v_mul_f32_e32 v97, 0x37800000, v96
	v_cndmask_b32_e32 v96, v96, v97, vcc
	v_cmp_class_f32_e32 vcc, v197, v217
	s_nop 1
	v_cndmask_b32_e32 v197, v96, v197, vcc
	v_div_scale_f32 v96, s[0:1], v197, v197, 1.0
	v_rcp_f32_e32 v97, v96
	s_nop 0
	v_fma_f32 v98, -v96, v97, 1.0
	v_fmac_f32_e32 v97, v98, v97
	v_div_scale_f32 v98, vcc, 1.0, v197, 1.0
	v_mul_f32_e32 v99, v98, v97
	v_fma_f32 v100, -v96, v99, v98
	v_fmac_f32_e32 v99, v100, v97
	v_fma_f32 v96, -v96, v99, v98
	v_div_fmas_f32 v96, v96, v97, v99
	v_div_fixup_f32 v197, v96, v197, 1.0
	v_mul_f32_e32 v148, v148, v197
	v_mul_f32_e32 v149, v149, v197
	v_mul_f32_e32 v150, v150, v197
	v_mul_f32_e32 v151, v151, v197
	v_mul_f32_e32 v96, v2, v148
	v_cvt_pk_bf16_f32 v96, v96, s0
	v_mul_f32_e32 v97, v3, v149
	v_cvt_pk_bf16_f32 v97, v97, s0
	v_mul_f32_e32 v98, v4, v150
	v_cvt_pk_bf16_f32 v98, v98, s0
	v_mul_f32_e32 v99, v5, v151
	v_cvt_pk_bf16_f32 v99, v99, s0
	ds_write_b16 v19, v96 offset:10
	ds_write_b16 v19, v97 offset:282
	ds_write_b16 v19, v98 offset:554
	ds_write_b16 v19, v99 offset:826
	v_fmamk_f32 v198, v198, 0x3b800000, v216
	v_cmp_gt_f32_e32 vcc, s69, v198
	v_mul_f32_e32 v96, 0x4f800000, v198
	s_nop 0
	v_cndmask_b32_e32 v198, v198, v96, vcc
	v_sqrt_f32_e32 v96, v198
	s_nop 0
	v_add_u32_e32 v97, -1, v96
	v_fma_f32 v98, -v97, v96, v198
	v_cmp_ge_f32_e64 s[0:1], 0, v98
	v_add_u32_e32 v98, 1, v96
	s_nop 0
	v_cndmask_b32_e64 v97, v96, v97, s[0:1]
	v_fma_f32 v96, -v98, v96, v198
	v_cmp_lt_f32_e64 s[0:1], 0, v96
	s_nop 1
	v_cndmask_b32_e64 v96, v97, v98, s[0:1]
	v_mul_f32_e32 v97, 0x37800000, v96
	v_cndmask_b32_e32 v96, v96, v97, vcc
	v_cmp_class_f32_e32 vcc, v198, v217
	s_nop 1
	v_cndmask_b32_e32 v198, v96, v198, vcc
	v_div_scale_f32 v96, s[0:1], v198, v198, 1.0
	v_rcp_f32_e32 v97, v96
	s_nop 0
	v_fma_f32 v98, -v96, v97, 1.0
	v_fmac_f32_e32 v97, v98, v97
	v_div_scale_f32 v98, vcc, 1.0, v198, 1.0
	v_mul_f32_e32 v99, v98, v97
	v_fma_f32 v100, -v96, v99, v98
	v_fmac_f32_e32 v99, v100, v97
	v_fma_f32 v96, -v96, v99, v98
	v_div_fmas_f32 v96, v96, v97, v99
	v_div_fixup_f32 v198, v96, v198, 1.0
	v_mul_f32_e32 v152, v152, v198
	v_mul_f32_e32 v153, v153, v198
	v_mul_f32_e32 v154, v154, v198
	v_mul_f32_e32 v155, v155, v198
	v_mul_f32_e32 v96, v2, v152
	v_cvt_pk_bf16_f32 v96, v96, s0
	v_mul_f32_e32 v97, v3, v153
	v_cvt_pk_bf16_f32 v97, v97, s0
	v_mul_f32_e32 v98, v4, v154
	v_cvt_pk_bf16_f32 v98, v98, s0
	v_mul_f32_e32 v99, v5, v155
	v_cvt_pk_bf16_f32 v99, v99, s0
	ds_write_b16 v19, v96 offset:12
	ds_write_b16 v19, v97 offset:284
	ds_write_b16 v19, v98 offset:556
	ds_write_b16 v19, v99 offset:828
	v_fmamk_f32 v199, v199, 0x3b800000, v216
	v_cmp_gt_f32_e32 vcc, s69, v199
	v_mul_f32_e32 v96, 0x4f800000, v199
	s_nop 0
	v_cndmask_b32_e32 v199, v199, v96, vcc
	v_sqrt_f32_e32 v96, v199
	s_nop 0
	v_add_u32_e32 v97, -1, v96
	v_fma_f32 v98, -v97, v96, v199
	v_cmp_ge_f32_e64 s[0:1], 0, v98
	v_add_u32_e32 v98, 1, v96
	s_nop 0
	v_cndmask_b32_e64 v97, v96, v97, s[0:1]
	v_fma_f32 v96, -v98, v96, v199
	v_cmp_lt_f32_e64 s[0:1], 0, v96
	s_nop 1
	v_cndmask_b32_e64 v96, v97, v98, s[0:1]
	v_mul_f32_e32 v97, 0x37800000, v96
	v_cndmask_b32_e32 v96, v96, v97, vcc
	v_cmp_class_f32_e32 vcc, v199, v217
	s_nop 1
	v_cndmask_b32_e32 v199, v96, v199, vcc
	v_div_scale_f32 v96, s[0:1], v199, v199, 1.0
	v_rcp_f32_e32 v97, v96
	s_nop 0
	v_fma_f32 v98, -v96, v97, 1.0
	v_fmac_f32_e32 v97, v98, v97
	v_div_scale_f32 v98, vcc, 1.0, v199, 1.0
	v_mul_f32_e32 v99, v98, v97
	v_fma_f32 v100, -v96, v99, v98
	v_fmac_f32_e32 v99, v100, v97
	v_fma_f32 v96, -v96, v99, v98
	v_div_fmas_f32 v96, v96, v97, v99
	v_div_fixup_f32 v199, v96, v199, 1.0
	v_mul_f32_e32 v156, v156, v199
	v_mul_f32_e32 v157, v157, v199
	v_mul_f32_e32 v158, v158, v199
	v_mul_f32_e32 v159, v159, v199
	v_mul_f32_e32 v96, v2, v156
	v_cvt_pk_bf16_f32 v96, v96, s0
	v_mul_f32_e32 v97, v3, v157
	v_cvt_pk_bf16_f32 v97, v97, s0
	v_mul_f32_e32 v98, v4, v158
	v_cvt_pk_bf16_f32 v98, v98, s0
	v_mul_f32_e32 v99, v5, v159
	v_cvt_pk_bf16_f32 v99, v99, s0
	ds_write_b16 v19, v96 offset:14
	ds_write_b16 v19, v97 offset:286
	ds_write_b16 v19, v98 offset:558
	ds_write_b16 v19, v99 offset:830
	v_fmamk_f32 v200, v200, 0x3b800000, v216
	v_cmp_gt_f32_e32 vcc, s69, v200
	v_mul_f32_e32 v96, 0x4f800000, v200
	s_nop 0
	v_cndmask_b32_e32 v200, v200, v96, vcc
	v_sqrt_f32_e32 v96, v200
	s_nop 0
	v_add_u32_e32 v97, -1, v96
	v_fma_f32 v98, -v97, v96, v200
	v_cmp_ge_f32_e64 s[0:1], 0, v98
	v_add_u32_e32 v98, 1, v96
	s_nop 0
	v_cndmask_b32_e64 v97, v96, v97, s[0:1]
	v_fma_f32 v96, -v98, v96, v200
	v_cmp_lt_f32_e64 s[0:1], 0, v96
	s_nop 1
	v_cndmask_b32_e64 v96, v97, v98, s[0:1]
	v_mul_f32_e32 v97, 0x37800000, v96
	v_cndmask_b32_e32 v96, v96, v97, vcc
	v_cmp_class_f32_e32 vcc, v200, v217
	s_nop 1
	v_cndmask_b32_e32 v200, v96, v200, vcc
	v_div_scale_f32 v96, s[0:1], v200, v200, 1.0
	v_rcp_f32_e32 v97, v96
	s_nop 0
	v_fma_f32 v98, -v96, v97, 1.0
	v_fmac_f32_e32 v97, v98, v97
	v_div_scale_f32 v98, vcc, 1.0, v200, 1.0
	v_mul_f32_e32 v99, v98, v97
	v_fma_f32 v100, -v96, v99, v98
	v_fmac_f32_e32 v99, v100, v97
	v_fma_f32 v96, -v96, v99, v98
; __device__ __forceinline__ unsigned cvtpk_s(float lo, float hi) { typedef __bf16 bf16x2_t __attribute__((ext_vector_type(2))); f32x2 v = {lo, hi}; bf16x2_t b = __builtin_convertvector(v, bf16x2_t); return __builtin_bit_cast(unsigned, b); }
; __device__ __forceinline__ void sg_unit(const Params& P, int l, int chunk, char* shm, float* ssb) {
;     ...
;         const float rstd = 1.f / sqrtf(wave_sum((sq[0] + sq[1]) + (sq[2] + sq[3])) * (1.f / 256.f) + LN_EPS);
;         v = v * rstd * g4;
; #pragma unroll
;         for (int j = 0; j < 4; ++j) vt[(4 * lane + j) * SG_VT_PITCH + q] = (bf16_t)(at::cvtpk_s(v[j], 0.f) & 0xffffu);
	v_div_fmas_f32 v96, v96, v97, v99
	v_div_fixup_f32 v200, v96, v200, 1.0
	v_mul_f32_e32 v160, v160, v200
	v_mul_f32_e32 v161, v161, v200
	v_mul_f32_e32 v162, v162, v200
	v_mul_f32_e32 v163, v163, v200
	v_mul_f32_e32 v96, v2, v160
	v_cvt_pk_bf16_f32 v96, v96, s0
	v_mul_f32_e32 v97, v3, v161
	v_cvt_pk_bf16_f32 v97, v97, s0
	v_mul_f32_e32 v98, v4, v162
	v_cvt_pk_bf16_f32 v98, v98, s0
	v_mul_f32_e32 v99, v5, v163
	v_cvt_pk_bf16_f32 v99, v99, s0
	ds_write_b16 v19, v96 offset:16
	ds_write_b16 v19, v97 offset:288
	ds_write_b16 v19, v98 offset:560
	ds_write_b16 v19, v99 offset:832
	v_fmamk_f32 v201, v201, 0x3b800000, v216
	v_cmp_gt_f32_e32 vcc, s69, v201
	v_mul_f32_e32 v96, 0x4f800000, v201
	s_nop 0
	v_cndmask_b32_e32 v201, v201, v96, vcc
	v_sqrt_f32_e32 v96, v201
	s_nop 0
	v_add_u32_e32 v97, -1, v96
	v_fma_f32 v98, -v97, v96, v201
	v_cmp_ge_f32_e64 s[0:1], 0, v98
	v_add_u32_e32 v98, 1, v96
	s_nop 0
	v_cndmask_b32_e64 v97, v96, v97, s[0:1]
	v_fma_f32 v96, -v98, v96, v201
	v_cmp_lt_f32_e64 s[0:1], 0, v96
	s_nop 1
	v_cndmask_b32_e64 v96, v97, v98, s[0:1]
	v_mul_f32_e32 v97, 0x37800000, v96
	v_cndmask_b32_e32 v96, v96, v97, vcc
	v_cmp_class_f32_e32 vcc, v201, v217
	s_nop 1
	v_cndmask_b32_e32 v201, v96, v201, vcc
	v_div_scale_f32 v96, s[0:1], v201, v201, 1.0
	v_rcp_f32_e32 v97, v96
	s_nop 0
	v_fma_f32 v98, -v96, v97, 1.0
	v_fmac_f32_e32 v97, v98, v97
	v_div_scale_f32 v98, vcc, 1.0, v201, 1.0
	v_mul_f32_e32 v99, v98, v97
	v_fma_f32 v100, -v96, v99, v98
	v_fmac_f32_e32 v99, v100, v97
	v_fma_f32 v96, -v96, v99, v98
	v_div_fmas_f32 v96, v96, v97, v99
	v_div_fixup_f32 v201, v96, v201, 1.0
	v_mul_f32_e32 v164, v164, v201
	v_mul_f32_e32 v165, v165, v201
	v_mul_f32_e32 v166, v166, v201
	v_mul_f32_e32 v167, v167, v201
	v_mul_f32_e32 v96, v2, v164
	v_cvt_pk_bf16_f32 v96, v96, s0
	v_mul_f32_e32 v97, v3, v165
	v_cvt_pk_bf16_f32 v97, v97, s0
	v_mul_f32_e32 v98, v4, v166
	v_cvt_pk_bf16_f32 v98, v98, s0
	v_mul_f32_e32 v99, v5, v167
	v_cvt_pk_bf16_f32 v99, v99, s0
	ds_write_b16 v19, v96 offset:18
	ds_write_b16 v19, v97 offset:290
	ds_write_b16 v19, v98 offset:562
	ds_write_b16 v19, v99 offset:834
	v_fmamk_f32 v202, v202, 0x3b800000, v216
	v_cmp_gt_f32_e32 vcc, s69, v202
	v_mul_f32_e32 v96, 0x4f800000, v202
	s_nop 0
	v_cndmask_b32_e32 v202, v202, v96, vcc
	v_sqrt_f32_e32 v96, v202
	s_nop 0
	v_add_u32_e32 v97, -1, v96
	v_fma_f32 v98, -v97, v96, v202
	v_cmp_ge_f32_e64 s[0:1], 0, v98
	v_add_u32_e32 v98, 1, v96
	s_nop 0
	v_cndmask_b32_e64 v97, v96, v97, s[0:1]
	v_fma_f32 v96, -v98, v96, v202
	v_cmp_lt_f32_e64 s[0:1], 0, v96
	s_nop 1
	v_cndmask_b32_e64 v96, v97, v98, s[0:1]
	v_mul_f32_e32 v97, 0x37800000, v96
	v_cndmask_b32_e32 v96, v96, v97, vcc
	v_cmp_class_f32_e32 vcc, v202, v217
	s_nop 1
	v_cndmask_b32_e32 v202, v96, v202, vcc
	v_div_scale_f32 v96, s[0:1], v202, v202, 1.0
	v_rcp_f32_e32 v97, v96
	s_nop 0
	v_fma_f32 v98, -v96, v97, 1.0
	v_fmac_f32_e32 v97, v98, v97
	v_div_scale_f32 v98, vcc, 1.0, v202, 1.0
	v_mul_f32_e32 v99, v98, v97
	v_fma_f32 v100, -v96, v99, v98
	v_fmac_f32_e32 v99, v100, v97
	v_fma_f32 v96, -v96, v99, v98
	v_div_fmas_f32 v96, v96, v97, v99
	v_div_fixup_f32 v202, v96, v202, 1.0
	v_mul_f32_e32 v168, v168, v202
	v_mul_f32_e32 v169, v169, v202
	v_mul_f32_e32 v170, v170, v202
	v_mul_f32_e32 v171, v171, v202
	v_mul_f32_e32 v96, v2, v168
	v_cvt_pk_bf16_f32 v96, v96, s0
	v_mul_f32_e32 v97, v3, v169
	v_cvt_pk_bf16_f32 v97, v97, s0
	v_mul_f32_e32 v98, v4, v170
	v_cvt_pk_bf16_f32 v98, v98, s0
	v_mul_f32_e32 v99, v5, v171
	v_cvt_pk_bf16_f32 v99, v99, s0
	ds_write_b16 v19, v96 offset:20
	ds_write_b16 v19, v97 offset:292
	ds_write_b16 v19, v98 offset:564
	ds_write_b16 v19, v99 offset:836
	v_fmamk_f32 v203, v203, 0x3b800000, v216
	v_cmp_gt_f32_e32 vcc, s69, v203
	v_mul_f32_e32 v96, 0x4f800000, v203
	s_nop 0
	v_cndmask_b32_e32 v203, v203, v96, vcc
	v_sqrt_f32_e32 v96, v203
	s_nop 0
	v_add_u32_e32 v97, -1, v96
	v_fma_f32 v98, -v97, v96, v203
	v_cmp_ge_f32_e64 s[0:1], 0, v98
	v_add_u32_e32 v98, 1, v96
	s_nop 0
	v_cndmask_b32_e64 v97, v96, v97, s[0:1]
	v_fma_f32 v96, -v98, v96, v203
	v_cmp_lt_f32_e64 s[0:1], 0, v96
	s_nop 1
	v_cndmask_b32_e64 v96, v97, v98, s[0:1]
	v_mul_f32_e32 v97, 0x37800000, v96
	v_cndmask_b32_e32 v96, v96, v97, vcc
	v_cmp_class_f32_e32 vcc, v203, v217
	s_nop 1
	v_cndmask_b32_e32 v203, v96, v203, vcc
	v_div_scale_f32 v96, s[0:1], v203, v203, 1.0
	v_rcp_f32_e32 v97, v96
	s_nop 0
	v_fma_f32 v98, -v96, v97, 1.0
	v_fmac_f32_e32 v97, v98, v97
	v_div_scale_f32 v98, vcc, 1.0, v203, 1.0
	v_mul_f32_e32 v99, v98, v97
	v_fma_f32 v100, -v96, v99, v98
	v_fmac_f32_e32 v99, v100, v97
	v_fma_f32 v96, -v96, v99, v98
	v_div_fmas_f32 v96, v96, v97, v99
	v_div_fixup_f32 v203, v96, v203, 1.0
	v_mul_f32_e32 v172, v172, v203
	v_mul_f32_e32 v173, v173, v203
	v_mul_f32_e32 v174, v174, v203
	v_mul_f32_e32 v175, v175, v203
	v_mul_f32_e32 v96, v2, v172
	v_cvt_pk_bf16_f32 v96, v96, s0
	v_mul_f32_e32 v97, v3, v173
	v_cvt_pk_bf16_f32 v97, v97, s0
	v_mul_f32_e32 v98, v4, v174
	v_cvt_pk_bf16_f32 v98, v98, s0
	v_mul_f32_e32 v99, v5, v175
	v_cvt_pk_bf16_f32 v99, v99, s0
	ds_write_b16 v19, v96 offset:22
	ds_write_b16 v19, v97 offset:294
	ds_write_b16 v19, v98 offset:566
	ds_write_b16 v19, v99 offset:838
	v_fmamk_f32 v204, v204, 0x3b800000, v216
	v_cmp_gt_f32_e32 vcc, s69, v204
	v_mul_f32_e32 v96, 0x4f800000, v204
	s_nop 0
	v_cndmask_b32_e32 v204, v204, v96, vcc
	v_sqrt_f32_e32 v96, v204
	s_nop 0
	v_add_u32_e32 v97, -1, v96
	v_fma_f32 v98, -v97, v96, v204
	v_cmp_ge_f32_e64 s[0:1], 0, v98
	v_add_u32_e32 v98, 1, v96
	s_nop 0
	v_cndmask_b32_e64 v97, v96, v97, s[0:1]
	v_fma_f32 v96, -v98, v96, v204
	v_cmp_lt_f32_e64 s[0:1], 0, v96
	s_nop 1
	v_cndmask_b32_e64 v96, v97, v98, s[0:1]
; __device__ __forceinline__ unsigned cvtpk_s(float lo, float hi) { typedef __bf16 bf16x2_t __attribute__((ext_vector_type(2))); f32x2 v = {lo, hi}; bf16x2_t b = __builtin_convertvector(v, bf16x2_t); return __builtin_bit_cast(unsigned, b); }
; __device__ __forceinline__ void sg_unit(const Params& P, int l, int chunk, char* shm, float* ssb) {
;     ...
;         v = v * rstd * g4;
; #pragma unroll
;         for (int j = 0; j < 4; ++j) vt[(4 * lane + j) * SG_VT_PITCH + q] = (bf16_t)(at::cvtpk_s(v[j], 0.f) & 0xffffu);
;     }
;     asm volatile("s_waitcnt lgkmcnt(0)\n\ts_barrier" ::: "memory");
;     ...
;     const bf16_t* Wg = Wsb + (size_t)g * 128 * 128;
; #pragma unroll
;     for (int k0 = 0; k0 < 128; k0 += 16) {
;         bf16x8 af[2], bfr[2];
; #pragma unroll
;         for (int pt = 0; pt < 2; ++pt) af[pt] = *(const bf16x8*)(Wg + (size_t)(64 * ph + 32 * pt + r32) * 128 + k0 + 8 * hi);
	v_mul_f32_e32 v97, 0x37800000, v96
	v_cndmask_b32_e32 v96, v96, v97, vcc
	v_cmp_class_f32_e32 vcc, v204, v217
	s_nop 1
	v_cndmask_b32_e32 v204, v96, v204, vcc
	v_div_scale_f32 v96, s[0:1], v204, v204, 1.0
	v_rcp_f32_e32 v97, v96
	s_nop 0
	v_fma_f32 v98, -v96, v97, 1.0
	v_fmac_f32_e32 v97, v98, v97
	v_div_scale_f32 v98, vcc, 1.0, v204, 1.0
	v_mul_f32_e32 v99, v98, v97
	v_fma_f32 v100, -v96, v99, v98
	v_fmac_f32_e32 v99, v100, v97
	v_fma_f32 v96, -v96, v99, v98
	v_div_fmas_f32 v96, v96, v97, v99
	v_div_fixup_f32 v204, v96, v204, 1.0
	v_mul_f32_e32 v176, v176, v204
	v_mul_f32_e32 v177, v177, v204
	v_mul_f32_e32 v178, v178, v204
	v_mul_f32_e32 v179, v179, v204
	v_mul_f32_e32 v96, v2, v176
	v_cvt_pk_bf16_f32 v96, v96, s0
	v_mul_f32_e32 v97, v3, v177
	v_cvt_pk_bf16_f32 v97, v97, s0
	v_mul_f32_e32 v98, v4, v178
	v_cvt_pk_bf16_f32 v98, v98, s0
	v_mul_f32_e32 v99, v5, v179
	v_cvt_pk_bf16_f32 v99, v99, s0
	ds_write_b16 v19, v96 offset:24
	ds_write_b16 v19, v97 offset:296
	ds_write_b16 v19, v98 offset:568
	ds_write_b16 v19, v99 offset:840
	v_fmamk_f32 v205, v205, 0x3b800000, v216
	v_cmp_gt_f32_e32 vcc, s69, v205
	v_mul_f32_e32 v96, 0x4f800000, v205
	s_nop 0
	v_cndmask_b32_e32 v205, v205, v96, vcc
	v_sqrt_f32_e32 v96, v205
	s_nop 0
	v_add_u32_e32 v97, -1, v96
	v_fma_f32 v98, -v97, v96, v205
	v_cmp_ge_f32_e64 s[0:1], 0, v98
	v_add_u32_e32 v98, 1, v96
	s_nop 0
	v_cndmask_b32_e64 v97, v96, v97, s[0:1]
	v_fma_f32 v96, -v98, v96, v205
	v_cmp_lt_f32_e64 s[0:1], 0, v96
	s_nop 1
	v_cndmask_b32_e64 v96, v97, v98, s[0:1]
	v_mul_f32_e32 v97, 0x37800000, v96
	v_cndmask_b32_e32 v96, v96, v97, vcc
	v_cmp_class_f32_e32 vcc, v205, v217
	s_nop 1
	v_cndmask_b32_e32 v205, v96, v205, vcc
	v_div_scale_f32 v96, s[0:1], v205, v205, 1.0
	v_rcp_f32_e32 v97, v96
	s_nop 0
	v_fma_f32 v98, -v96, v97, 1.0
	v_fmac_f32_e32 v97, v98, v97
	v_div_scale_f32 v98, vcc, 1.0, v205, 1.0
	v_mul_f32_e32 v99, v98, v97
	v_fma_f32 v100, -v96, v99, v98
	v_fmac_f32_e32 v99, v100, v97
	v_fma_f32 v96, -v96, v99, v98
	v_div_fmas_f32 v96, v96, v97, v99
	v_div_fixup_f32 v205, v96, v205, 1.0
	v_mul_f32_e32 v180, v180, v205
	v_mul_f32_e32 v181, v181, v205
	v_mul_f32_e32 v182, v182, v205
	v_mul_f32_e32 v183, v183, v205
	v_mul_f32_e32 v96, v2, v180
	v_cvt_pk_bf16_f32 v96, v96, s0
	v_mul_f32_e32 v97, v3, v181
	v_cvt_pk_bf16_f32 v97, v97, s0
	v_mul_f32_e32 v98, v4, v182
	v_cvt_pk_bf16_f32 v98, v98, s0
	v_mul_f32_e32 v99, v5, v183
	v_cvt_pk_bf16_f32 v99, v99, s0
	ds_write_b16 v19, v96 offset:26
	ds_write_b16 v19, v97 offset:298
	ds_write_b16 v19, v98 offset:570
	ds_write_b16 v19, v99 offset:842
	v_fmamk_f32 v206, v206, 0x3b800000, v216
	v_cmp_gt_f32_e32 vcc, s69, v206
	v_mul_f32_e32 v96, 0x4f800000, v206
	s_nop 0
	v_cndmask_b32_e32 v206, v206, v96, vcc
	v_sqrt_f32_e32 v96, v206
	s_nop 0
	v_add_u32_e32 v97, -1, v96
	v_fma_f32 v98, -v97, v96, v206
	v_cmp_ge_f32_e64 s[0:1], 0, v98
	v_add_u32_e32 v98, 1, v96
	s_nop 0
	v_cndmask_b32_e64 v97, v96, v97, s[0:1]
	v_fma_f32 v96, -v98, v96, v206
	v_cmp_lt_f32_e64 s[0:1], 0, v96
	s_nop 1
	v_cndmask_b32_e64 v96, v97, v98, s[0:1]
	v_mul_f32_e32 v97, 0x37800000, v96
	v_cndmask_b32_e32 v96, v96, v97, vcc
	v_cmp_class_f32_e32 vcc, v206, v217
	s_nop 1
	v_cndmask_b32_e32 v206, v96, v206, vcc
	v_div_scale_f32 v96, s[0:1], v206, v206, 1.0
	v_rcp_f32_e32 v97, v96
	s_nop 0
	v_fma_f32 v98, -v96, v97, 1.0
	v_fmac_f32_e32 v97, v98, v97
	v_div_scale_f32 v98, vcc, 1.0, v206, 1.0
	v_mul_f32_e32 v99, v98, v97
	v_fma_f32 v100, -v96, v99, v98
	v_fmac_f32_e32 v99, v100, v97
	v_fma_f32 v96, -v96, v99, v98
	v_div_fmas_f32 v96, v96, v97, v99
	v_div_fixup_f32 v206, v96, v206, 1.0
	v_mul_f32_e32 v184, v184, v206
	v_mul_f32_e32 v185, v185, v206
	v_mul_f32_e32 v186, v186, v206
	v_mul_f32_e32 v187, v187, v206
	v_mul_f32_e32 v96, v2, v184
	v_cvt_pk_bf16_f32 v96, v96, s0
	v_mul_f32_e32 v97, v3, v185
	v_cvt_pk_bf16_f32 v97, v97, s0
	v_mul_f32_e32 v98, v4, v186
	v_cvt_pk_bf16_f32 v98, v98, s0
	v_mul_f32_e32 v99, v5, v187
	v_cvt_pk_bf16_f32 v99, v99, s0
	ds_write_b16 v19, v96 offset:28
	ds_write_b16 v19, v97 offset:300
	ds_write_b16 v19, v98 offset:572
	ds_write_b16 v19, v99 offset:844
	v_fmamk_f32 v207, v207, 0x3b800000, v216
	v_cmp_gt_f32_e32 vcc, s69, v207
	v_mul_f32_e32 v96, 0x4f800000, v207
	s_nop 0
	v_cndmask_b32_e32 v207, v207, v96, vcc
	v_sqrt_f32_e32 v96, v207
	s_nop 0
	v_add_u32_e32 v97, -1, v96
	v_fma_f32 v98, -v97, v96, v207
	v_cmp_ge_f32_e64 s[0:1], 0, v98
	v_add_u32_e32 v98, 1, v96
	s_nop 0
	v_cndmask_b32_e64 v97, v96, v97, s[0:1]
	v_fma_f32 v96, -v98, v96, v207
	v_cmp_lt_f32_e64 s[0:1], 0, v96
	s_nop 1
	v_cndmask_b32_e64 v96, v97, v98, s[0:1]
	v_mul_f32_e32 v97, 0x37800000, v96
	v_cndmask_b32_e32 v96, v96, v97, vcc
	v_cmp_class_f32_e32 vcc, v207, v217
	s_nop 1
	v_cndmask_b32_e32 v207, v96, v207, vcc
	v_div_scale_f32 v96, s[0:1], v207, v207, 1.0
	v_rcp_f32_e32 v97, v96
	s_nop 0
	v_fma_f32 v98, -v96, v97, 1.0
	v_fmac_f32_e32 v97, v98, v97
	v_div_scale_f32 v98, vcc, 1.0, v207, 1.0
	v_mul_f32_e32 v99, v98, v97
	v_fma_f32 v100, -v96, v99, v98
	v_fmac_f32_e32 v99, v100, v97
	v_fma_f32 v96, -v96, v99, v98
	v_div_fmas_f32 v96, v96, v97, v99
	v_div_fixup_f32 v207, v96, v207, 1.0
	v_mul_f32_e32 v188, v188, v207
	v_mul_f32_e32 v189, v189, v207
	v_mul_f32_e32 v190, v190, v207
	v_mul_f32_e32 v191, v191, v207
	v_mul_f32_e32 v96, v2, v188
	v_cvt_pk_bf16_f32 v96, v96, s0
	v_mul_f32_e32 v97, v3, v189
	v_cvt_pk_bf16_f32 v97, v97, s0
	v_mul_f32_e32 v98, v4, v190
	v_cvt_pk_bf16_f32 v98, v98, s0
	v_mul_f32_e32 v99, v5, v191
	v_cvt_pk_bf16_f32 v99, v99, s0
	ds_write_b16 v19, v96 offset:30
	ds_write_b16 v19, v97 offset:302
	ds_write_b16 v19, v98 offset:574
	ds_write_b16 v19, v99 offset:846
	s_lshl_b32 s7, s3, 7
	s_add_u32 s10, s4, 0x200000
	s_addc_u32 s11, s5, 0
	s_ashr_i32 s4, s6, 7
	s_ashr_i32 s5, s4, 31
	s_bfe_u32 s1, s6, 0x10006
	s_lshl_b64 s[8:9], s[4:5], 15
	v_readlane_b32 s0, v252, 20
	v_and_b32_e32 v14, 31, v12
	v_lshrrev_b32_e32 v15, 5, v13
	s_add_u32 s8, s0, s8
	v_readlane_b32 s0, v252, 21
	s_addc_u32 s9, s0, s9
	v_lshlrev_b32_e32 v0, 4, v15
	v_lshlrev_b32_e32 v2, 8, v14
	v_lshl_add_u64 v[4:5], s[8:9], 0, v[0:1]
	v_lshl_or_b32 v10, s1, 14, v2
	v_mov_b32_e32 v11, v1
	s_waitcnt lgkmcnt(0)
	s_barrier
; __device__ __forceinline__ void sg_unit(const Params& P, int l, int chunk, char* shm, float* ssb) {
;     ...
;     const bf16_t* Wg = Wsb + (size_t)g * 128 * 128;
; #pragma unroll
;     for (int k0 = 0; k0 < 128; k0 += 16) {
;         bf16x8 af[2], bfr[2];
; #pragma unroll
;         for (int pt = 0; pt < 2; ++pt) af[pt] = *(const bf16x8*)(Wg + (size_t)(64 * ph + 32 * pt + r32) * 128 + k0 + 8 * hi);
; #pragma unroll
;         for (int ct = 0; ct < 2; ++ct) bfr[ct] = *(const bf16x8*)(vt + (64 * g + 32 * ct + r32) * SG_VT_PITCH + k0 + 8 * hi);
; #pragma unroll
;         for (int pt = 0; pt < 2; ++pt)
; #pragma unroll
;             for (int ct = 0; ct < 2; ++ct) acc[pt][ct] = __builtin_amdgcn_mfma_f32_32x32x16_bf16(af[pt], bfr[ct], acc[pt][ct], 0, 0, 0);
;     }
	v_lshl_add_u64 v[2:3], v[4:5], 0, v[10:11]
	global_load_dwordx4 v[6:9], v[2:3], off
	v_or_b32_e32 v10, 0x2000, v10
	v_lshl_add_u64 v[4:5], v[4:5], 0, v[10:11]
	global_load_dwordx4 v[18:21], v[4:5], off
	s_lshl_b32 s0, s4, 6
	v_or_b32_e32 v22, s0, v14
	s_movk_i32 s4, 0x110
	v_mul_lo_u32 v10, v22, s4
	v_add3_u32 v0, 0, v0, v10
	ds_read_b128 v[22:25], v0 offset:8704
	ds_read_b128 v[26:29], v0
	ds_read_b128 v[84:87], v0 offset:32
	s_and_b32 s4, s6, 0xffffff80
	s_ashr_i32 s5, s4, 31
	s_lshl_b64 s[4:5], s[4:5], 2
	v_readlane_b32 s6, v252, 22
	s_add_u32 s4, s6, s4
	v_readlane_b32 s6, v252, 23
	s_addc_u32 s5, s6, s5
	s_lshl_b32 s6, s1, 6
	s_or_b32 s86, s6, s7
	s_ashr_i32 s1, s0, 31
	s_lshl_b32 s2, s2, 12
	s_add_i32 s2, s2, 0
	s_lshl_b64 s[0:1], s[0:1], 1
	s_add_i32 s2, s2, 0x12000
	v_lshlrev_b32_e32 v10, 1, v14
	s_waitcnt vmcnt(1) lgkmcnt(1)
	v_mfma_f32_32x32x16_bf16 v[66:81], v[6:9], v[26:29], 0
	v_mfma_f32_32x32x16_bf16 v[50:65], v[6:9], v[22:25], 0
	global_load_dwordx4 v[6:9], v[2:3], off offset:32
	global_load_dwordx4 v[88:91], v[4:5], off offset:32
	ds_read_b128 v[92:95], v0 offset:8736
	s_waitcnt vmcnt(2)
	v_mfma_f32_32x32x16_bf16 v[34:49], v[18:21], v[26:29], 0
	v_mfma_f32_32x32x16_bf16 v[18:33], v[18:21], v[22:25], 0
	s_waitcnt vmcnt(1) lgkmcnt(1)
	v_mfma_f32_32x32x16_bf16 v[66:81], v[6:9], v[84:87], v[66:81]
	s_waitcnt lgkmcnt(0)
	v_mfma_f32_32x32x16_bf16 v[50:65], v[6:9], v[92:95], v[50:65]
	s_waitcnt vmcnt(0)
	v_mfma_f32_32x32x16_bf16 v[34:49], v[88:91], v[84:87], v[34:49]
	global_load_dwordx4 v[6:9], v[2:3], off offset:64
	global_load_dwordx4 v[84:87], v[4:5], off offset:64
	v_mfma_f32_32x32x16_bf16 v[18:33], v[88:91], v[92:95], v[18:33]
	ds_read_b128 v[88:91], v0 offset:64
	ds_read_b128 v[92:95], v0 offset:8768
	s_waitcnt vmcnt(1) lgkmcnt(1)
	v_mfma_f32_32x32x16_bf16 v[66:81], v[6:9], v[88:91], v[66:81]
	s_waitcnt lgkmcnt(0)
	v_mfma_f32_32x32x16_bf16 v[50:65], v[6:9], v[92:95], v[50:65]
	s_waitcnt vmcnt(0)
	v_mfma_f32_32x32x16_bf16 v[34:49], v[84:87], v[88:91], v[34:49]
	v_mfma_f32_32x32x16_bf16 v[18:33], v[84:87], v[92:95], v[18:33]
	global_load_dwordx4 v[6:9], v[2:3], off offset:96
	global_load_dwordx4 v[84:87], v[4:5], off offset:96
	ds_read_b128 v[88:91], v0 offset:96
	ds_read_b128 v[92:95], v0 offset:8800
	s_waitcnt vmcnt(1) lgkmcnt(1)
	v_mfma_f32_32x32x16_bf16 v[66:81], v[6:9], v[88:91], v[66:81]
	s_waitcnt lgkmcnt(0)
	v_mfma_f32_32x32x16_bf16 v[50:65], v[6:9], v[92:95], v[50:65]
	s_waitcnt vmcnt(0)
	v_mfma_f32_32x32x16_bf16 v[34:49], v[84:87], v[88:91], v[34:49]
	v_mfma_f32_32x32x16_bf16 v[18:33], v[84:87], v[92:95], v[18:33]
	global_load_dwordx4 v[6:9], v[2:3], off offset:128
	global_load_dwordx4 v[84:87], v[4:5], off offset:128
	ds_read_b128 v[88:91], v0 offset:128
	ds_read_b128 v[92:95], v0 offset:8832
	s_waitcnt vmcnt(1) lgkmcnt(1)
	v_mfma_f32_32x32x16_bf16 v[66:81], v[6:9], v[88:91], v[66:81]
	s_waitcnt lgkmcnt(0)
	v_mfma_f32_32x32x16_bf16 v[50:65], v[6:9], v[92:95], v[50:65]
	s_waitcnt vmcnt(0)
	v_mfma_f32_32x32x16_bf16 v[34:49], v[84:87], v[88:91], v[34:49]
	v_mfma_f32_32x32x16_bf16 v[18:33], v[84:87], v[92:95], v[18:33]
	global_load_dwordx4 v[6:9], v[2:3], off offset:160
	global_load_dwordx4 v[84:87], v[4:5], off offset:160
	ds_read_b128 v[88:91], v0 offset:160
	ds_read_b128 v[92:95], v0 offset:8864
	s_waitcnt vmcnt(1) lgkmcnt(1)
	v_mfma_f32_32x32x16_bf16 v[66:81], v[6:9], v[88:91], v[66:81]
	s_waitcnt lgkmcnt(0)
	v_mfma_f32_32x32x16_bf16 v[50:65], v[6:9], v[92:95], v[50:65]
	s_waitcnt vmcnt(0)
	v_mfma_f32_32x32x16_bf16 v[34:49], v[84:87], v[88:91], v[34:49]
	v_mfma_f32_32x32x16_bf16 v[18:33], v[84:87], v[92:95], v[18:33]
	global_load_dwordx4 v[6:9], v[2:3], off offset:192
	global_load_dwordx4 v[84:87], v[4:5], off offset:192
	ds_read_b128 v[88:91], v0 offset:192
	ds_read_b128 v[92:95], v0 offset:8896
	s_waitcnt vmcnt(1) lgkmcnt(1)
	v_mfma_f32_32x32x16_bf16 v[66:81], v[6:9], v[88:91], v[66:81]
	s_waitcnt lgkmcnt(0)
	v_mfma_f32_32x32x16_bf16 v[50:65], v[6:9], v[92:95], v[50:65]
	global_load_dwordx4 v[6:9], v[2:3], off offset:224
	s_nop 0
	global_load_dwordx4 v[2:5], v[4:5], off offset:224
	s_waitcnt vmcnt(2)
	v_mfma_f32_32x32x16_bf16 v[34:49], v[84:87], v[88:91], v[34:49]
	v_mfma_f32_32x32x16_bf16 v[18:33], v[84:87], v[92:95], v[18:33]
	ds_read_b128 v[84:87], v0 offset:224
	ds_read_b128 v[88:91], v0 offset:8928
	v_lshl_or_b32 v0, v15, 2, s6
	s_waitcnt vmcnt(1) lgkmcnt(1)
	v_mfma_f32_32x32x16_bf16 v[66:81], v[6:9], v[84:87], v[66:81]
	s_waitcnt vmcnt(0)
	v_mfma_f32_32x32x16_bf16 v[34:49], v[2:5], v[84:87], v[34:49]
	v_or_b32_e32 v86, s7, v0
	v_readlane_b32 s6, v254, 8
	v_and_b32_e32 v87, 7, v12
	v_lshlrev_b32_e32 v12, 2, v0
	v_mul_lo_u32 v0, v86, s80
	v_readlane_b32 s7, v254, 9
	v_lshlrev_b32_e32 v14, 4, v87
	s_waitcnt lgkmcnt(0)
; __device__ __forceinline__ float bf2f(unsigned short h) { return __uint_as_float(((unsigned)h) << 16); }
; __device__ __forceinline__ int crow(int r, int hi) { return (r & 3) + 8 * (r >> 2) + 4 * hi; }
; __device__ __forceinline__ void sg_unit(const Params& P, int l, int chunk, char* shm, float* ssb) {
;     ...
;             for (int ct = 0; ct < 2; ++ct) acc[pt][ct] = __builtin_amdgcn_mfma_f32_32x32x16_bf16(af[pt], bfr[ct], acc[pt][ct], 0, 0, 0);
;     }
;     const float* bs = P.b_s + (size_t)l * 512 + g * 128;
;     float ones[16];
; #pragma unroll
;     for (int r = 0; r < 16; ++r) ones[r] = 1.0f;
; #pragma unroll
;     for (int pt = 0; pt < 2; ++pt) {
;         f32x16 o[2];
; #pragma unroll
;         for (int r = 0; r < 16; ++r) { const int p = 64 * ph + 32 * pt + at::crow(r, hi); const float bp = bs[p];
; #pragma unroll
;             for (int ct = 0; ct < 2; ++ct) { const float uu = bf2f(qkv[(size_t)(R0 + p) * DIN + C_U + 64 * g + 32 * ct + r32]); o[ct][r] = uu * (acc[pt][ct][r] + bp); } }
	v_mfma_f32_32x32x16_bf16 v[50:65], v[6:9], v[88:91], v[50:65]
	v_mov_b32_e32 v9, v1
	v_cmp_eq_u32_e32 vcc, 0, v87
	v_mov_b32_e32 v7, v1
	v_mfma_f32_32x32x16_bf16 v[18:33], v[2:5], v[88:91], v[18:33]
	v_lshl_add_u64 v[90:91], s[6:7], 0, v[0:1]
	v_lshlrev_b32_e32 v2, 9, v15
	v_lshrrev_b32_e32 v89, 3, v13
	v_lshl_add_u64 v[90:91], v[90:91], 0, s[0:1]
	v_add3_u32 v85, s2, v2, v10
	v_add_u32_e32 v88, s2, v14
	v_lshlrev_b32_e32 v2, 7, v89
	v_lshl_add_u64 v[90:91], v[90:91], 0, v[10:11]
	v_add_u32_e32 v84, v88, v2
	v_mov_b32_e32 v192, v10
	v_mov_b32_e32 v193, v1
	global_load_dwordx4 v[160:163], v12, s[4:5]
	global_load_dwordx4 v[164:167], v12, s[4:5] offset:32
	global_load_dwordx4 v[168:171], v12, s[4:5] offset:64
	global_load_dwordx4 v[172:175], v12, s[4:5] offset:96
	global_load_dwordx4 v[176:179], v12, s[4:5] offset:128
	global_load_dwordx4 v[180:183], v12, s[4:5] offset:160
	global_load_dwordx4 v[184:187], v12, s[4:5] offset:192
	global_load_dwordx4 v[188:191], v12, s[4:5] offset:224
	v_or_b32_e32 v194, 0, v86
	v_mul_lo_u32 v194, v194, s80
	v_mov_b32_e32 v195, v1
	v_lshl_add_u64 v[194:195], s[6:7], 0, v[194:195]
	v_lshl_add_u64 v[194:195], v[194:195], 0, s[0:1]
	v_lshl_add_u64 v[194:195], v[194:195], 0, v[192:193]
	global_load_ushort v96, v[194:195], off offset:1024
	global_load_ushort v97, v[194:195], off offset:1088
	v_or_b32_e32 v196, 1, v86
	v_mul_lo_u32 v196, v196, s80
	v_mov_b32_e32 v197, v1
	v_lshl_add_u64 v[196:197], s[6:7], 0, v[196:197]
	v_lshl_add_u64 v[196:197], v[196:197], 0, s[0:1]
	v_lshl_add_u64 v[196:197], v[196:197], 0, v[192:193]
	global_load_ushort v98, v[196:197], off offset:1024
	global_load_ushort v99, v[196:197], off offset:1088
	v_or_b32_e32 v194, 2, v86
	v_mul_lo_u32 v194, v194, s80
	v_mov_b32_e32 v195, v1
	v_lshl_add_u64 v[194:195], s[6:7], 0, v[194:195]
	v_lshl_add_u64 v[194:195], v[194:195], 0, s[0:1]
	v_lshl_add_u64 v[194:195], v[194:195], 0, v[192:193]
	global_load_ushort v100, v[194:195], off offset:1024
	global_load_ushort v101, v[194:195], off offset:1088
	v_or_b32_e32 v196, 3, v86
	v_mul_lo_u32 v196, v196, s80
	v_mov_b32_e32 v197, v1
	v_lshl_add_u64 v[196:197], s[6:7], 0, v[196:197]
	v_lshl_add_u64 v[196:197], v[196:197], 0, s[0:1]
	v_lshl_add_u64 v[196:197], v[196:197], 0, v[192:193]
	global_load_ushort v102, v[196:197], off offset:1024
	global_load_ushort v103, v[196:197], off offset:1088
	v_or_b32_e32 v194, 8, v86
	v_mul_lo_u32 v194, v194, s80
	v_mov_b32_e32 v195, v1
	v_lshl_add_u64 v[194:195], s[6:7], 0, v[194:195]
	v_lshl_add_u64 v[194:195], v[194:195], 0, s[0:1]
	v_lshl_add_u64 v[194:195], v[194:195], 0, v[192:193]
	global_load_ushort v104, v[194:195], off offset:1024
	global_load_ushort v105, v[194:195], off offset:1088
	v_or_b32_e32 v196, 9, v86
	v_mul_lo_u32 v196, v196, s80
	v_mov_b32_e32 v197, v1
	v_lshl_add_u64 v[196:197], s[6:7], 0, v[196:197]
	v_lshl_add_u64 v[196:197], v[196:197], 0, s[0:1]
	v_lshl_add_u64 v[196:197], v[196:197], 0, v[192:193]
	global_load_ushort v106, v[196:197], off offset:1024
	global_load_ushort v107, v[196:197], off offset:1088
	v_or_b32_e32 v194, 10, v86
	v_mul_lo_u32 v194, v194, s80
	v_mov_b32_e32 v195, v1
	v_lshl_add_u64 v[194:195], s[6:7], 0, v[194:195]
	v_lshl_add_u64 v[194:195], v[194:195], 0, s[0:1]
	v_lshl_add_u64 v[194:195], v[194:195], 0, v[192:193]
	global_load_ushort v108, v[194:195], off offset:1024
	global_load_ushort v109, v[194:195], off offset:1088
	v_or_b32_e32 v196, 11, v86
	v_mul_lo_u32 v196, v196, s80
	v_mov_b32_e32 v197, v1
	v_lshl_add_u64 v[196:197], s[6:7], 0, v[196:197]
	v_lshl_add_u64 v[196:197], v[196:197], 0, s[0:1]
	v_lshl_add_u64 v[196:197], v[196:197], 0, v[192:193]
	global_load_ushort v110, v[196:197], off offset:1024
	global_load_ushort v111, v[196:197], off offset:1088
	v_or_b32_e32 v194, 16, v86
	v_mul_lo_u32 v194, v194, s80
	v_mov_b32_e32 v195, v1
	v_lshl_add_u64 v[194:195], s[6:7], 0, v[194:195]
	v_lshl_add_u64 v[194:195], v[194:195], 0, s[0:1]
	v_lshl_add_u64 v[194:195], v[194:195], 0, v[192:193]
	global_load_ushort v112, v[194:195], off offset:1024
	global_load_ushort v113, v[194:195], off offset:1088
	v_or_b32_e32 v196, 17, v86
	v_mul_lo_u32 v196, v196, s80
	v_mov_b32_e32 v197, v1
	v_lshl_add_u64 v[196:197], s[6:7], 0, v[196:197]
	v_lshl_add_u64 v[196:197], v[196:197], 0, s[0:1]
	v_lshl_add_u64 v[196:197], v[196:197], 0, v[192:193]
	global_load_ushort v114, v[196:197], off offset:1024
	global_load_ushort v115, v[196:197], off offset:1088
	v_or_b32_e32 v194, 18, v86
	v_mul_lo_u32 v194, v194, s80
	v_mov_b32_e32 v195, v1
	v_lshl_add_u64 v[194:195], s[6:7], 0, v[194:195]
	v_lshl_add_u64 v[194:195], v[194:195], 0, s[0:1]
	v_lshl_add_u64 v[194:195], v[194:195], 0, v[192:193]
	global_load_ushort v116, v[194:195], off offset:1024
	global_load_ushort v117, v[194:195], off offset:1088
	v_or_b32_e32 v196, 19, v86
	v_mul_lo_u32 v196, v196, s80
	v_mov_b32_e32 v197, v1
	v_lshl_add_u64 v[196:197], s[6:7], 0, v[196:197]
	v_lshl_add_u64 v[196:197], v[196:197], 0, s[0:1]
	v_lshl_add_u64 v[196:197], v[196:197], 0, v[192:193]
	global_load_ushort v118, v[196:197], off offset:1024
	global_load_ushort v119, v[196:197], off offset:1088
	v_or_b32_e32 v194, 24, v86
	v_mul_lo_u32 v194, v194, s80
	v_mov_b32_e32 v195, v1
	v_lshl_add_u64 v[194:195], s[6:7], 0, v[194:195]
	v_lshl_add_u64 v[194:195], v[194:195], 0, s[0:1]
	v_lshl_add_u64 v[194:195], v[194:195], 0, v[192:193]
	global_load_ushort v120, v[194:195], off offset:1024
	global_load_ushort v121, v[194:195], off offset:1088
	v_or_b32_e32 v196, 25, v86
	v_mul_lo_u32 v196, v196, s80
	v_mov_b32_e32 v197, v1
	v_lshl_add_u64 v[196:197], s[6:7], 0, v[196:197]
	v_lshl_add_u64 v[196:197], v[196:197], 0, s[0:1]
; __device__ __forceinline__ float bf2f(unsigned short h) { return __uint_as_float(((unsigned)h) << 16); }
; __device__ __forceinline__ int crow(int r, int hi) { return (r & 3) + 8 * (r >> 2) + 4 * hi; }
; __device__ __forceinline__ void sg_unit(const Params& P, int l, int chunk, char* shm, float* ssb) {
;     ...
;     for (int pt = 0; pt < 2; ++pt) {
;         f32x16 o[2];
; #pragma unroll
;         for (int r = 0; r < 16; ++r) { const int p = 64 * ph + 32 * pt + at::crow(r, hi); const float bp = bs[p];
; #pragma unroll
;             for (int ct = 0; ct < 2; ++ct) { const float uu = bf2f(qkv[(size_t)(R0 + p) * DIN + C_U + 64 * g + 32 * ct + r32]); o[ct][r] = uu * (acc[pt][ct][r] + bp); } }
	v_lshl_add_u64 v[196:197], v[196:197], 0, v[192:193]
	global_load_ushort v122, v[196:197], off offset:1024
	global_load_ushort v123, v[196:197], off offset:1088
	v_or_b32_e32 v194, 26, v86
	v_mul_lo_u32 v194, v194, s80
	v_mov_b32_e32 v195, v1
	v_lshl_add_u64 v[194:195], s[6:7], 0, v[194:195]
	v_lshl_add_u64 v[194:195], v[194:195], 0, s[0:1]
	v_lshl_add_u64 v[194:195], v[194:195], 0, v[192:193]
	global_load_ushort v124, v[194:195], off offset:1024
	global_load_ushort v125, v[194:195], off offset:1088
	v_or_b32_e32 v196, 27, v86
	v_mul_lo_u32 v196, v196, s80
	v_mov_b32_e32 v197, v1
	v_lshl_add_u64 v[196:197], s[6:7], 0, v[196:197]
	v_lshl_add_u64 v[196:197], v[196:197], 0, s[0:1]
	v_lshl_add_u64 v[196:197], v[196:197], 0, v[192:193]
	global_load_ushort v126, v[196:197], off offset:1024
	global_load_ushort v127, v[196:197], off offset:1088
	v_or_b32_e32 v194, 32, v86
	v_mul_lo_u32 v194, v194, s80
	v_mov_b32_e32 v195, v1
	v_lshl_add_u64 v[194:195], s[6:7], 0, v[194:195]
	v_lshl_add_u64 v[194:195], v[194:195], 0, s[0:1]
	v_lshl_add_u64 v[194:195], v[194:195], 0, v[192:193]
	global_load_ushort v128, v[194:195], off offset:1024
	global_load_ushort v129, v[194:195], off offset:1088
	v_or_b32_e32 v196, 33, v86
	v_mul_lo_u32 v196, v196, s80
	v_mov_b32_e32 v197, v1
	v_lshl_add_u64 v[196:197], s[6:7], 0, v[196:197]
	v_lshl_add_u64 v[196:197], v[196:197], 0, s[0:1]
	v_lshl_add_u64 v[196:197], v[196:197], 0, v[192:193]
	global_load_ushort v130, v[196:197], off offset:1024
	global_load_ushort v131, v[196:197], off offset:1088
	v_or_b32_e32 v194, 34, v86
	v_mul_lo_u32 v194, v194, s80
	v_mov_b32_e32 v195, v1
	v_lshl_add_u64 v[194:195], s[6:7], 0, v[194:195]
	v_lshl_add_u64 v[194:195], v[194:195], 0, s[0:1]
	v_lshl_add_u64 v[194:195], v[194:195], 0, v[192:193]
	global_load_ushort v132, v[194:195], off offset:1024
	global_load_ushort v133, v[194:195], off offset:1088
	v_or_b32_e32 v196, 35, v86
	v_mul_lo_u32 v196, v196, s80
	v_mov_b32_e32 v197, v1
	v_lshl_add_u64 v[196:197], s[6:7], 0, v[196:197]
	v_lshl_add_u64 v[196:197], v[196:197], 0, s[0:1]
	v_lshl_add_u64 v[196:197], v[196:197], 0, v[192:193]
	global_load_ushort v134, v[196:197], off offset:1024
	global_load_ushort v135, v[196:197], off offset:1088
	v_or_b32_e32 v194, 40, v86
	v_mul_lo_u32 v194, v194, s80
	v_mov_b32_e32 v195, v1
	v_lshl_add_u64 v[194:195], s[6:7], 0, v[194:195]
	v_lshl_add_u64 v[194:195], v[194:195], 0, s[0:1]
	v_lshl_add_u64 v[194:195], v[194:195], 0, v[192:193]
	global_load_ushort v136, v[194:195], off offset:1024
	global_load_ushort v137, v[194:195], off offset:1088
	v_or_b32_e32 v196, 41, v86
	v_mul_lo_u32 v196, v196, s80
	v_mov_b32_e32 v197, v1
	v_lshl_add_u64 v[196:197], s[6:7], 0, v[196:197]
	v_lshl_add_u64 v[196:197], v[196:197], 0, s[0:1]
	v_lshl_add_u64 v[196:197], v[196:197], 0, v[192:193]
	global_load_ushort v138, v[196:197], off offset:1024
	global_load_ushort v139, v[196:197], off offset:1088
	v_or_b32_e32 v194, 42, v86
	v_mul_lo_u32 v194, v194, s80
	v_mov_b32_e32 v195, v1
	v_lshl_add_u64 v[194:195], s[6:7], 0, v[194:195]
	v_lshl_add_u64 v[194:195], v[194:195], 0, s[0:1]
	v_lshl_add_u64 v[194:195], v[194:195], 0, v[192:193]
	global_load_ushort v140, v[194:195], off offset:1024
	global_load_ushort v141, v[194:195], off offset:1088
	v_or_b32_e32 v196, 43, v86
	v_mul_lo_u32 v196, v196, s80
	v_mov_b32_e32 v197, v1
	v_lshl_add_u64 v[196:197], s[6:7], 0, v[196:197]
	v_lshl_add_u64 v[196:197], v[196:197], 0, s[0:1]
	v_lshl_add_u64 v[196:197], v[196:197], 0, v[192:193]
	global_load_ushort v142, v[196:197], off offset:1024
	global_load_ushort v143, v[196:197], off offset:1088
	v_or_b32_e32 v194, 48, v86
	v_mul_lo_u32 v194, v194, s80
	v_mov_b32_e32 v195, v1
	v_lshl_add_u64 v[194:195], s[6:7], 0, v[194:195]
	v_lshl_add_u64 v[194:195], v[194:195], 0, s[0:1]
	v_lshl_add_u64 v[194:195], v[194:195], 0, v[192:193]
	global_load_ushort v144, v[194:195], off offset:1024
	global_load_ushort v145, v[194:195], off offset:1088
	v_or_b32_e32 v196, 49, v86
	v_mul_lo_u32 v196, v196, s80
	v_mov_b32_e32 v197, v1
	v_lshl_add_u64 v[196:197], s[6:7], 0, v[196:197]
	v_lshl_add_u64 v[196:197], v[196:197], 0, s[0:1]
	v_lshl_add_u64 v[196:197], v[196:197], 0, v[192:193]
	global_load_ushort v146, v[196:197], off offset:1024
	global_load_ushort v147, v[196:197], off offset:1088
	v_or_b32_e32 v194, 50, v86
	v_mul_lo_u32 v194, v194, s80
	v_mov_b32_e32 v195, v1
	v_lshl_add_u64 v[194:195], s[6:7], 0, v[194:195]
	v_lshl_add_u64 v[194:195], v[194:195], 0, s[0:1]
	v_lshl_add_u64 v[194:195], v[194:195], 0, v[192:193]
	global_load_ushort v148, v[194:195], off offset:1024
	global_load_ushort v149, v[194:195], off offset:1088
	v_or_b32_e32 v196, 51, v86
	v_mul_lo_u32 v196, v196, s80
	v_mov_b32_e32 v197, v1
	v_lshl_add_u64 v[196:197], s[6:7], 0, v[196:197]
	v_lshl_add_u64 v[196:197], v[196:197], 0, s[0:1]
	v_lshl_add_u64 v[196:197], v[196:197], 0, v[192:193]
	global_load_ushort v150, v[196:197], off offset:1024
	global_load_ushort v151, v[196:197], off offset:1088
	v_or_b32_e32 v194, 56, v86
	v_mul_lo_u32 v194, v194, s80
	v_mov_b32_e32 v195, v1
	v_lshl_add_u64 v[194:195], s[6:7], 0, v[194:195]
	v_lshl_add_u64 v[194:195], v[194:195], 0, s[0:1]
	v_lshl_add_u64 v[194:195], v[194:195], 0, v[192:193]
	global_load_ushort v152, v[194:195], off offset:1024
	global_load_ushort v153, v[194:195], off offset:1088
	v_or_b32_e32 v196, 57, v86
	v_mul_lo_u32 v196, v196, s80
	v_mov_b32_e32 v197, v1
	v_lshl_add_u64 v[196:197], s[6:7], 0, v[196:197]
	v_lshl_add_u64 v[196:197], v[196:197], 0, s[0:1]
	v_lshl_add_u64 v[196:197], v[196:197], 0, v[192:193]
	global_load_ushort v154, v[196:197], off offset:1024
	global_load_ushort v155, v[196:197], off offset:1088
	v_or_b32_e32 v194, 58, v86
	v_mul_lo_u32 v194, v194, s80
	v_mov_b32_e32 v195, v1
	v_lshl_add_u64 v[194:195], s[6:7], 0, v[194:195]
	v_lshl_add_u64 v[194:195], v[194:195], 0, s[0:1]
	v_lshl_add_u64 v[194:195], v[194:195], 0, v[192:193]
	global_load_ushort v156, v[194:195], off offset:1024
	global_load_ushort v157, v[194:195], off offset:1088
	v_or_b32_e32 v196, 59, v86
	v_mul_lo_u32 v196, v196, s80
	v_mov_b32_e32 v197, v1
	v_lshl_add_u64 v[196:197], s[6:7], 0, v[196:197]
	v_lshl_add_u64 v[196:197], v[196:197], 0, s[0:1]
	v_lshl_add_u64 v[196:197], v[196:197], 0, v[192:193]
	global_load_ushort v158, v[196:197], off offset:1024
	global_load_ushort v159, v[196:197], off offset:1088
	s_waitcnt vmcnt(0)
; __device__ __forceinline__ float bf2f(unsigned short h) { return __uint_as_float(((unsigned)h) << 16); }
; __device__ __forceinline__ int crow(int r, int hi) { return (r & 3) + 8 * (r >> 2) + 4 * hi; }
; __device__ __forceinline__ void sg_unit(const Params& P, int l, int chunk, char* shm, float* ssb) {
;     ...
;     for (int pt = 0; pt < 2; ++pt) {
;         f32x16 o[2];
; #pragma unroll
;         for (int r = 0; r < 16; ++r) { const int p = 64 * ph + 32 * pt + at::crow(r, hi); const float bp = bs[p];
; #pragma unroll
;             for (int ct = 0; ct < 2; ++ct) { const float uu = bf2f(qkv[(size_t)(R0 + p) * DIN + C_U + 64 * g + 32 * ct + r32]); o[ct][r] = uu * (acc[pt][ct][r] + bp); } }
	v_mov_b64_e32 v[2:3], v[160:161]
	v_mov_b64_e32 v[4:5], v[162:163]
	v_mov_b32_e32 v0, v96
	v_lshlrev_b32_e32 v8, 11, v89
	v_lshlrev_b32_e32 v6, 4, v89
	v_add_f32_e32 v13, v66, v2
	v_lshlrev_b32_e32 v0, 16, v0
	v_mul_f32_e32 v13, v13, v0
	v_mov_b32_e32 v0, v97
	v_add_f32_e32 v2, v50, v2
	v_add_f32_e32 v66, v68, v4
	v_lshlrev_b32_e32 v0, 16, v0
	v_mul_f32_e32 v15, v2, v0
	v_or_b32_e32 v0, 1, v86
	v_mul_lo_u32 v0, v0, s80
	v_lshl_add_u64 v[90:91], s[6:7], 0, v[0:1]
	v_lshl_add_u64 v[90:91], v[90:91], 0, s[0:1]
	v_lshl_add_u64 v[90:91], v[90:91], 0, v[10:11]
	v_mov_b32_e32 v0, v98
	v_add_f32_e32 v2, v67, v3
	v_lshlrev_b32_e32 v0, 16, v0
	v_mul_f32_e32 v50, v2, v0
	v_mov_b32_e32 v0, v99
	v_add_f32_e32 v2, v51, v3
	v_lshlrev_b32_e32 v0, 16, v0
	v_mul_f32_e32 v51, v2, v0
	v_or_b32_e32 v0, 2, v86
	v_mul_lo_u32 v0, v0, s80
	v_lshl_add_u64 v[2:3], s[6:7], 0, v[0:1]
	v_lshl_add_u64 v[2:3], v[2:3], 0, s[0:1]
	v_lshl_add_u64 v[2:3], v[2:3], 0, v[10:11]
	v_mov_b32_e32 v0, v100
	v_lshlrev_b32_e32 v0, 16, v0
	v_mul_f32_e32 v66, v66, v0
	v_mov_b32_e32 v0, v101
	v_add_f32_e32 v2, v52, v4
	v_add_f32_e32 v4, v69, v5
	v_lshlrev_b32_e32 v0, 16, v0
	v_mul_f32_e32 v52, v2, v0
	v_or_b32_e32 v0, 3, v86
	v_mul_lo_u32 v0, v0, s80
	v_lshl_add_u64 v[2:3], s[6:7], 0, v[0:1]
	v_lshl_add_u64 v[2:3], v[2:3], 0, s[0:1]
	v_lshl_add_u64 v[2:3], v[2:3], 0, v[10:11]
	v_mov_b32_e32 v0, v102
	v_lshlrev_b32_e32 v0, 16, v0
	v_mul_f32_e32 v67, v4, v0
	v_mov_b32_e32 v0, v103
	v_add_f32_e32 v2, v53, v5
	v_lshlrev_b32_e32 v0, 16, v0
	v_mul_f32_e32 v53, v2, v0
	v_or_b32_e32 v0, 8, v86
	v_mul_lo_u32 v0, v0, s80
	v_lshl_add_u64 v[68:69], s[6:7], 0, v[0:1]
	v_lshl_add_u64 v[68:69], v[68:69], 0, s[0:1]
	v_lshl_add_u64 v[90:91], v[68:69], 0, v[10:11]
	v_mov_b64_e32 v[2:3], v[164:165]
	v_mov_b64_e32 v[4:5], v[166:167]
	v_mov_b32_e32 v0, v104
	v_add_f32_e32 v68, v70, v2
	v_lshlrev_b32_e32 v0, 16, v0
	v_mul_f32_e32 v68, v68, v0
	v_mov_b32_e32 v0, v105
	v_add_f32_e32 v2, v54, v2
	v_add_f32_e32 v70, v72, v4
	v_lshlrev_b32_e32 v0, 16, v0
	v_mul_f32_e32 v54, v2, v0
	v_or_b32_e32 v0, 9, v86
	v_mul_lo_u32 v0, v0, s80
	v_lshl_add_u64 v[90:91], s[6:7], 0, v[0:1]
	v_lshl_add_u64 v[90:91], v[90:91], 0, s[0:1]
	v_lshl_add_u64 v[90:91], v[90:91], 0, v[10:11]
	v_mov_b32_e32 v0, v106
	v_add_f32_e32 v2, v71, v3
	v_lshlrev_b32_e32 v0, 16, v0
	v_mul_f32_e32 v69, v2, v0
	v_mov_b32_e32 v0, v107
	v_add_f32_e32 v2, v55, v3
	v_lshlrev_b32_e32 v0, 16, v0
	v_mul_f32_e32 v55, v2, v0
	v_or_b32_e32 v0, 10, v86
	v_mul_lo_u32 v0, v0, s80
	v_lshl_add_u64 v[2:3], s[6:7], 0, v[0:1]
	v_lshl_add_u64 v[2:3], v[2:3], 0, s[0:1]
	v_lshl_add_u64 v[2:3], v[2:3], 0, v[10:11]
	v_mov_b32_e32 v0, v108
	v_lshlrev_b32_e32 v0, 16, v0
	v_mul_f32_e32 v70, v70, v0
	v_mov_b32_e32 v0, v109
	v_add_f32_e32 v2, v56, v4
	v_add_f32_e32 v4, v73, v5
	v_lshlrev_b32_e32 v0, 16, v0
	v_mul_f32_e32 v56, v2, v0
	v_or_b32_e32 v0, 11, v86
	v_mul_lo_u32 v0, v0, s80
	v_lshl_add_u64 v[2:3], s[6:7], 0, v[0:1]
	v_lshl_add_u64 v[2:3], v[2:3], 0, s[0:1]
	v_lshl_add_u64 v[2:3], v[2:3], 0, v[10:11]
	v_mov_b32_e32 v0, v110
	v_lshlrev_b32_e32 v0, 16, v0
	v_mul_f32_e32 v71, v4, v0
	v_mov_b32_e32 v0, v111
	v_add_f32_e32 v2, v57, v5
	v_lshlrev_b32_e32 v0, 16, v0
	v_mul_f32_e32 v57, v2, v0
	v_or_b32_e32 v0, 16, v86
	v_mul_lo_u32 v0, v0, s80
	v_lshl_add_u64 v[72:73], s[6:7], 0, v[0:1]
	v_lshl_add_u64 v[72:73], v[72:73], 0, s[0:1]
	v_lshl_add_u64 v[90:91], v[72:73], 0, v[10:11]
	v_mov_b64_e32 v[2:3], v[168:169]
	v_mov_b64_e32 v[4:5], v[170:171]
	v_mov_b32_e32 v0, v112
	v_add_f32_e32 v72, v74, v2
	v_lshlrev_b32_e32 v0, 16, v0
	v_mul_f32_e32 v72, v72, v0
	v_mov_b32_e32 v0, v113
	v_add_f32_e32 v2, v58, v2
	v_add_f32_e32 v74, v76, v4
	v_lshlrev_b32_e32 v0, 16, v0
	v_mul_f32_e32 v58, v2, v0
	v_or_b32_e32 v0, 17, v86
	v_mul_lo_u32 v0, v0, s80
	v_lshl_add_u64 v[90:91], s[6:7], 0, v[0:1]
	v_lshl_add_u64 v[90:91], v[90:91], 0, s[0:1]
	v_lshl_add_u64 v[90:91], v[90:91], 0, v[10:11]
	v_mov_b32_e32 v0, v114
	v_add_f32_e32 v2, v75, v3
	v_lshlrev_b32_e32 v0, 16, v0
	v_mul_f32_e32 v73, v2, v0
	v_mov_b32_e32 v0, v115
	v_add_f32_e32 v2, v59, v3
	v_lshlrev_b32_e32 v0, 16, v0
	v_mul_f32_e32 v59, v2, v0
	v_or_b32_e32 v0, 18, v86
	v_mul_lo_u32 v0, v0, s80
	v_lshl_add_u64 v[2:3], s[6:7], 0, v[0:1]
	v_lshl_add_u64 v[2:3], v[2:3], 0, s[0:1]
	v_lshl_add_u64 v[2:3], v[2:3], 0, v[10:11]
	v_mov_b32_e32 v0, v116
	v_lshlrev_b32_e32 v0, 16, v0
	v_mul_f32_e32 v74, v74, v0
	v_mov_b32_e32 v0, v117
	v_add_f32_e32 v2, v60, v4
	v_add_f32_e32 v4, v77, v5
	v_lshlrev_b32_e32 v0, 16, v0
	v_mul_f32_e32 v60, v2, v0
	v_or_b32_e32 v0, 19, v86
	v_mul_lo_u32 v0, v0, s80
	v_lshl_add_u64 v[2:3], s[6:7], 0, v[0:1]
	v_lshl_add_u64 v[2:3], v[2:3], 0, s[0:1]
	v_lshl_add_u64 v[2:3], v[2:3], 0, v[10:11]
	v_mov_b32_e32 v0, v118
	v_lshlrev_b32_e32 v0, 16, v0
	v_mul_f32_e32 v75, v4, v0
	v_mov_b32_e32 v0, v119
	v_add_f32_e32 v2, v61, v5
	v_lshlrev_b32_e32 v0, 16, v0
	v_mul_f32_e32 v61, v2, v0
	v_or_b32_e32 v0, 24, v86
	v_mul_lo_u32 v0, v0, s80
	v_lshl_add_u64 v[76:77], s[6:7], 0, v[0:1]
	v_lshl_add_u64 v[76:77], v[76:77], 0, s[0:1]
	v_lshl_add_u64 v[90:91], v[76:77], 0, v[10:11]
; __device__ __forceinline__ float bf2f(unsigned short h) { return __uint_as_float(((unsigned)h) << 16); }
; __device__ __forceinline__ int crow(int r, int hi) { return (r & 3) + 8 * (r >> 2) + 4 * hi; }
; __device__ __forceinline__ unsigned cvtpk_s(float lo, float hi) { typedef __bf16 bf16x2_t __attribute__((ext_vector_type(2))); f32x2 v = {lo, hi}; bf16x2_t b = __builtin_convertvector(v, bf16x2_t); return __builtin_bit_cast(unsigned, b); }
; __device__ __forceinline__ void store_tile(const f32x16* o, const float* rli, bf16_t* stg, bf16_t* Ow, int pitch, float* ss, int lane, int r32, int hi) {
; #pragma unroll
;     for (int r = 0; r < 16; ++r) { const int orow = crow(r, hi);
; #pragma unroll
;         for (int d0 = 0; d0 < 2; ++d0) stg[orow * 64 + d0 * 32 + r32] = (bf16_t)(cvtpk_s(o[d0][r] * rli[r], 0.f) & 0xffffu); }
;     asm volatile("s_waitcnt lgkmcnt(0)" ::: "memory");
; #pragma unroll
;     for (int i = 0; i < 4; ++i) { const int row = i * 8 + (lane >> 3), ch = lane & 7; const u32x4 v = *(const u32x4*)(stg + row * 64 + ch * 8);
;         { const bf16_t* gp_ = Ow + (long)row * pitch + ch * 8; asm volatile("global_store_dwordx4 %0, %1, off sc0 sc1\n\ts_nop 1" :: "v"(gp_), "v"(v) : "memory"); }
;         float s = 0.f;
; #pragma unroll
;         for (int j = 0; j < 4; ++j) { const float a = __uint_as_float(v[j] << 16), b = __uint_as_float(v[j] & 0xffff0000u); s += a * a + b * b; }
;         s += __shfl_xor(s, 1); s += __shfl_xor(s, 2); s += __shfl_xor(s, 4);
;         if (ch == 0) atomicAdd(ss + (long)row * 4, s); }
;     asm volatile("s_waitcnt lgkmcnt(0)" ::: "memory");
; __device__ __forceinline__ void sg_unit(const Params& P, int l, int chunk, char* shm, float* ssb) {
;     ...
;     for (int pt = 0; pt < 2; ++pt) {
;         f32x16 o[2];
; #pragma unroll
;         for (int r = 0; r < 16; ++r) { const int p = 64 * ph + 32 * pt + at::crow(r, hi); const float bp = bs[p];
; #pragma unroll
;             for (int ct = 0; ct < 2; ++ct) { const float uu = bf2f(qkv[(size_t)(R0 + p) * DIN + C_U + 64 * g + 32 * ct + r32]); o[ct][r] = uu * (acc[pt][ct][r] + bp); } }
;         const int prow = R0 + 64 * ph + 32 * pt;
;         at::store_tile(o, ones, (bf16_t*)(shm + SG_STAGE) + wid * 2048, omix + (size_t)prow * DM + 384 + 64 * g, DM, ssb + (size_t)prow * 4 + 1, lane, r32, hi);
	v_mov_b64_e32 v[2:3], v[172:173]
	v_mov_b64_e32 v[4:5], v[174:175]
	v_mov_b32_e32 v0, v120
	v_add_f32_e32 v76, v78, v2
	v_lshlrev_b32_e32 v0, 16, v0
	v_mul_f32_e32 v76, v76, v0
	v_mov_b32_e32 v0, v121
	v_add_f32_e32 v2, v62, v2
	v_add_f32_e32 v62, v79, v3
	v_add_f32_e32 v3, v63, v3
	v_add_f32_e32 v63, v80, v4
	v_add_f32_e32 v4, v64, v4
	v_lshlrev_b32_e32 v0, 16, v0
	v_mul_f32_e32 v2, v2, v0
	v_or_b32_e32 v0, 25, v86
	v_mul_lo_u32 v0, v0, s80
	v_lshl_add_u64 v[90:91], s[6:7], 0, v[0:1]
	v_lshl_add_u64 v[90:91], v[90:91], 0, s[0:1]
	v_lshl_add_u64 v[90:91], v[90:91], 0, v[10:11]
	v_mov_b32_e32 v0, v122
	v_cvt_pk_bf16_f32 v2, v2, s0
	ds_write_b16 v85, v2 offset:3136
	v_lshlrev_b32_e32 v0, 16, v0
	v_mul_f32_e32 v62, v62, v0
	v_mov_b32_e32 v0, v123
	v_cvt_pk_bf16_f32 v2, v62, s0
	ds_write_b16 v85, v2 offset:3200
	v_lshlrev_b32_e32 v0, 16, v0
	v_mul_f32_e32 v3, v3, v0
	v_or_b32_e32 v0, 26, v86
	v_mul_lo_u32 v0, v0, s80
	v_lshl_add_u64 v[78:79], s[6:7], 0, v[0:1]
	v_lshl_add_u64 v[78:79], v[78:79], 0, s[0:1]
	v_lshl_add_u64 v[78:79], v[78:79], 0, v[10:11]
	v_mov_b32_e32 v0, v124
	v_cvt_pk_bf16_f32 v2, v3, s0
	ds_write_b16 v85, v2 offset:3264
	v_lshlrev_b32_e32 v0, 16, v0
	v_mul_f32_e32 v63, v63, v0
	v_mov_b32_e32 v0, v125
	v_cvt_pk_bf16_f32 v2, v63, s0
	ds_write_b16 v85, v2 offset:3328
	v_lshlrev_b32_e32 v0, 16, v0
	v_mul_f32_e32 v4, v4, v0
	v_or_b32_e32 v0, 27, v86
	v_mul_lo_u32 v0, v0, s80
	v_lshl_add_u64 v[78:79], s[6:7], 0, v[0:1]
	v_lshl_add_u64 v[78:79], v[78:79], 0, s[0:1]
	v_lshl_add_u64 v[78:79], v[78:79], 0, v[10:11]
	v_mov_b32_e32 v0, v126
	v_add_f32_e32 v11, v81, v5
	v_add_f32_e32 v5, v65, v5
	s_lshl_b64 s[6:7], s[86:87], 11
	v_cvt_pk_bf16_f32 v2, v4, s0
	s_add_u32 s2, s76, s6
	ds_write_b16 v85, v2 offset:3392
	s_addc_u32 s6, s77, s7
	s_add_u32 s8, s2, s0
	s_addc_u32 s9, s6, s1
	s_lshl_b64 s[6:7], s[86:87], 4
	s_add_u32 s6, s10, s6
	s_addc_u32 s7, s11, s7
	v_lshlrev_b32_e32 v0, 16, v0
	v_mul_f32_e32 v0, v11, v0
	v_mov_b32_e32 v11, v127
	v_cvt_pk_bf16_f32 v0, v0, s0
	ds_write_b16 v85, v0 offset:3456
	v_lshlrev_b32_e32 v11, 16, v11
	v_mul_f32_e32 v5, v5, v11
	v_cvt_pk_bf16_f32 v11, v13, s0
	ds_write_b16 v85, v11
	v_cvt_pk_bf16_f32 v11, v15, s0
	ds_write_b16 v85, v11 offset:64
	v_cvt_pk_bf16_f32 v11, v50, s0
	ds_write_b16 v85, v11 offset:128
	v_cvt_pk_bf16_f32 v11, v51, s0
	ds_write_b16 v85, v11 offset:192
	v_cvt_pk_bf16_f32 v11, v66, s0
	ds_write_b16 v85, v11 offset:256
	v_cvt_pk_bf16_f32 v11, v52, s0
	ds_write_b16 v85, v11 offset:320
	v_cvt_pk_bf16_f32 v11, v67, s0
	ds_write_b16 v85, v11 offset:384
	v_cvt_pk_bf16_f32 v11, v53, s0
	ds_write_b16 v85, v11 offset:448
	v_cvt_pk_bf16_f32 v11, v68, s0
	ds_write_b16 v85, v11 offset:1024
	v_cvt_pk_bf16_f32 v11, v54, s0
	ds_write_b16 v85, v11 offset:1088
	v_cvt_pk_bf16_f32 v11, v69, s0
	ds_write_b16 v85, v11 offset:1152
	v_cvt_pk_bf16_f32 v11, v55, s0
	ds_write_b16 v85, v11 offset:1216
	v_cvt_pk_bf16_f32 v11, v70, s0
	ds_write_b16 v85, v11 offset:1280
	v_cvt_pk_bf16_f32 v11, v56, s0
	ds_write_b16 v85, v11 offset:1344
	v_cvt_pk_bf16_f32 v11, v71, s0
	ds_write_b16 v85, v11 offset:1408
	v_cvt_pk_bf16_f32 v11, v57, s0
	ds_write_b16 v85, v11 offset:1472
	v_cvt_pk_bf16_f32 v11, v72, s0
	ds_write_b16 v85, v11 offset:2048
	v_cvt_pk_bf16_f32 v11, v58, s0
	ds_write_b16 v85, v11 offset:2112
	v_cvt_pk_bf16_f32 v11, v73, s0
	ds_write_b16 v85, v11 offset:2176
	v_cvt_pk_bf16_f32 v11, v59, s0
	ds_write_b16 v85, v11 offset:2240
	v_cvt_pk_bf16_f32 v11, v74, s0
	ds_write_b16 v85, v11 offset:2304
	v_cvt_pk_bf16_f32 v11, v60, s0
	ds_write_b16 v85, v11 offset:2368
	v_cvt_pk_bf16_f32 v11, v75, s0
	ds_write_b16 v85, v11 offset:2432
	v_cvt_pk_bf16_f32 v11, v61, s0
	ds_write_b16 v85, v11 offset:2496
	v_cvt_pk_bf16_f32 v11, v76, s0
	v_cvt_pk_bf16_f32 v0, v5, s0
	ds_write_b16 v85, v11 offset:3072
	ds_write_b16 v85, v0 offset:3520
	s_waitcnt lgkmcnt(0)
	ds_read_b128 v[50:53], v84
	v_mov_b32_e32 v15, v1
	v_lshl_add_u64 v[2:3], s[8:9], 0, v[14:15]
	s_mov_b64 s[8:9], 0x12e40300
	v_lshl_add_u64 v[2:3], v[2:3], 0, s[8:9]
	v_lshl_add_u64 v[4:5], v[2:3], 0, v[8:9]
	s_waitcnt lgkmcnt(0)
	global_store_dwordx4 v[4:5], v[50:53], off sc0 sc1
	s_nop 1
	v_and_b32_e32 v4, 0xffff0000, v50
	v_lshlrev_b32_e32 v0, 16, v50
	v_mul_f32_e32 v4, v4, v4
	v_and_b32_e32 v5, 0xffff0000, v51
	v_fmac_f32_e32 v4, v0, v0
	v_lshlrev_b32_e32 v0, 16, v51
	v_mul_f32_e32 v5, v5, v5
	v_fmac_f32_e32 v5, v0, v0
	v_add_f32_e32 v0, v4, v5
	v_and_b32_e32 v5, 0xffff0000, v52
	v_lshlrev_b32_e32 v4, 16, v52
	v_mul_f32_e32 v5, v5, v5
	v_fmac_f32_e32 v5, v4, v4
	v_add_f32_e32 v0, v5, v0
	v_and_b32_e32 v5, 0xffff0000, v53
	v_lshlrev_b32_e32 v4, 16, v53
	v_mul_f32_e32 v5, v5, v5
	v_fmac_f32_e32 v5, v4, v4
	v_add_f32_e32 v0, v5, v0
	ds_bpermute_b32 v4, v17, v0
	s_waitcnt lgkmcnt(0)
	v_add_f32_e32 v0, v0, v4
	ds_bpermute_b32 v4, v83, v0
	s_waitcnt lgkmcnt(0)
	v_add_f32_e32 v0, v0, v4
	ds_bpermute_b32 v4, v82, v0
	s_and_saveexec_b64 s[8:9], vcc
	s_cbranch_execz .LBB0_562
	v_lshl_add_u64 v[14:15], s[6:7], 0, v[6:7]
	s_waitcnt lgkmcnt(0)
	v_add_f32_e32 v0, v0, v4
	flat_atomic_add_f32 v[14:15], v0 offset:4

; __device__ __forceinline__ float bf2f(unsigned short h) { return __uint_as_float(((unsigned)h) << 16); }
; __device__ __forceinline__ int crow(int r, int hi) { return (r & 3) + 8 * (r >> 2) + 4 * hi; }
; __device__ __forceinline__ void sg_unit(const Params& P, int l, int chunk, char* shm, float* ssb) {
;     ...
;     for (int pt = 0; pt < 2; ++pt) {
;         f32x16 o[2];
; #pragma unroll
;         for (int r = 0; r < 16; ++r) { const int p = 64 * ph + 32 * pt + at::crow(r, hi); const float bp = bs[p];
; #pragma unroll
;             for (int ct = 0; ct < 2; ++ct) { const float uu = bf2f(qkv[(size_t)(R0 + p) * DIN + C_U + 64 * g + 32 * ct + r32]); o[ct][r] = uu * (acc[pt][ct][r] + bp); } }
.LBB0_568:
	s_or_b64 exec, exec, s[4:5]
	v_or_b32_e32 v11, 32, v86
	v_readlane_b32 s4, v254, 8
	v_mul_lo_u32 v62, v11, s80
	v_mov_b32_e32 v63, v1
	v_readlane_b32 s5, v254, 9
	v_mov_b32_e32 v11, v1
	s_waitcnt lgkmcnt(0)
	s_waitcnt lgkmcnt(0)
	v_mov_b64_e32 v[2:3], v[176:177]
	v_mov_b64_e32 v[4:5], v[178:179]
	v_lshl_add_u64 v[62:63], s[4:5], 0, v[62:63]
	v_lshl_add_u64 v[62:63], v[62:63], 0, s[0:1]
	v_lshl_add_u64 v[62:63], v[62:63], 0, v[10:11]
	v_mov_b32_e32 v64, v128
	s_or_b32 s86, s86, 32
	v_mov_b32_e32 v62, v129
	v_mov_b32_e32 v63, v1
	v_lshlrev_b32_e32 v61, 3, v87
	v_add_f32_e32 v34, v34, v2
	v_add_f32_e32 v2, v18, v2
	v_add_f32_e32 v35, v35, v3
	v_add_f32_e32 v3, v19, v3
	v_add_f32_e32 v36, v36, v4
	v_lshlrev_b32_e32 v64, 16, v64
	v_lshlrev_b32_e32 v62, 16, v62
	v_mul_f32_e32 v18, v2, v62
	v_or_b32_e32 v2, 33, v86
	v_mul_lo_u32 v62, v2, s80
	v_lshl_add_u64 v[62:63], s[4:5], 0, v[62:63]
	v_lshl_add_u64 v[62:63], v[62:63], 0, s[0:1]
	v_lshl_add_u64 v[62:63], v[62:63], 0, v[10:11]
	v_mov_b32_e32 v2, v130
	v_mul_f32_e32 v34, v34, v64
	v_add_f32_e32 v37, v37, v5
	v_lshlrev_b32_e32 v2, 16, v2
	v_mul_f32_e32 v35, v35, v2
	v_mov_b32_e32 v2, v131
	v_mov_b32_e32 v63, v1
	v_lshlrev_b32_e32 v2, 16, v2
	v_mul_f32_e32 v19, v3, v2
	v_or_b32_e32 v2, 34, v86
	v_mul_lo_u32 v2, v2, s80
	v_mov_b32_e32 v3, v1
	v_lshl_add_u64 v[2:3], s[4:5], 0, v[2:3]
	v_lshl_add_u64 v[2:3], v[2:3], 0, s[0:1]
	v_lshl_add_u64 v[2:3], v[2:3], 0, v[10:11]
	v_mov_b32_e32 v62, v132
	v_lshlrev_b32_e32 v62, 16, v62
	v_mov_b32_e32 v2, v133
	v_add_f32_e32 v3, v20, v4
	v_mul_f32_e32 v36, v36, v62
	v_or_b32_e32 v62, 40, v86
	v_mul_lo_u32 v62, v62, s80
	v_lshl_add_u64 v[62:63], s[4:5], 0, v[62:63]
	v_lshl_add_u64 v[62:63], v[62:63], 0, s[0:1]
	v_lshl_add_u64 v[62:63], v[62:63], 0, v[10:11]
	v_mov_b32_e32 v64, v136
	v_lshlrev_b32_e32 v2, 16, v2
	v_mul_f32_e32 v20, v3, v2
	v_or_b32_e32 v2, 35, v86
	v_mul_lo_u32 v2, v2, s80
	v_mov_b32_e32 v3, v1
	v_lshl_add_u64 v[2:3], s[4:5], 0, v[2:3]
	v_lshl_add_u64 v[2:3], v[2:3], 0, s[0:1]
	v_lshl_add_u64 v[2:3], v[2:3], 0, v[10:11]
	v_mov_b32_e32 v4, v134
	v_lshlrev_b32_e32 v64, 16, v64
	v_mov_b32_e32 v2, v135
	v_lshlrev_b32_e32 v4, 16, v4
	v_mov_b32_e32 v62, v137
	v_lshlrev_b32_e32 v2, 16, v2
	v_add_f32_e32 v3, v21, v5
	v_mul_f32_e32 v37, v37, v4
	v_mul_f32_e32 v21, v3, v2
	v_mov_b64_e32 v[2:3], v[180:181]
	v_mov_b64_e32 v[4:5], v[182:183]
	v_mov_b32_e32 v63, v1
	v_lshlrev_b32_e32 v62, 16, v62
	v_add_f32_e32 v38, v38, v2
	v_add_f32_e32 v2, v22, v2
	v_mul_f32_e32 v22, v2, v62
	v_or_b32_e32 v2, 41, v86
	v_mul_lo_u32 v62, v2, s80
	v_lshl_add_u64 v[62:63], s[4:5], 0, v[62:63]
	v_lshl_add_u64 v[62:63], v[62:63], 0, s[0:1]
	v_lshl_add_u64 v[62:63], v[62:63], 0, v[10:11]
	v_mov_b32_e32 v2, v138
	v_add_f32_e32 v39, v39, v3
	v_add_f32_e32 v3, v23, v3
	v_add_f32_e32 v40, v40, v4
	v_mul_f32_e32 v38, v38, v64
	v_add_f32_e32 v41, v41, v5
	v_lshlrev_b32_e32 v2, 16, v2
	v_mul_f32_e32 v39, v39, v2
	v_mov_b32_e32 v2, v139
	v_mov_b32_e32 v63, v1
	v_lshlrev_b32_e32 v2, 16, v2
	v_mul_f32_e32 v23, v3, v2
	v_or_b32_e32 v2, 42, v86
	v_mul_lo_u32 v2, v2, s80
	v_mov_b32_e32 v3, v1
	v_lshl_add_u64 v[2:3], s[4:5], 0, v[2:3]
	v_lshl_add_u64 v[2:3], v[2:3], 0, s[0:1]
	v_lshl_add_u64 v[2:3], v[2:3], 0, v[10:11]
	v_mov_b32_e32 v62, v140
	v_lshlrev_b32_e32 v62, 16, v62
	v_mov_b32_e32 v2, v141
	v_add_f32_e32 v3, v24, v4
	v_mul_f32_e32 v40, v40, v62
	v_or_b32_e32 v62, 48, v86
	v_mul_lo_u32 v62, v62, s80
	v_lshl_add_u64 v[62:63], s[4:5], 0, v[62:63]
	v_lshl_add_u64 v[62:63], v[62:63], 0, s[0:1]
	v_lshl_add_u64 v[62:63], v[62:63], 0, v[10:11]
	v_mov_b32_e32 v64, v144
	v_lshlrev_b32_e32 v2, 16, v2
	v_mul_f32_e32 v24, v3, v2
	v_or_b32_e32 v2, 43, v86
	v_mul_lo_u32 v2, v2, s80
	v_mov_b32_e32 v3, v1
	v_lshl_add_u64 v[2:3], s[4:5], 0, v[2:3]
	v_lshl_add_u64 v[2:3], v[2:3], 0, s[0:1]
	v_lshl_add_u64 v[2:3], v[2:3], 0, v[10:11]
	v_mov_b32_e32 v4, v142
	v_lshlrev_b32_e32 v64, 16, v64
	v_mov_b32_e32 v2, v143
	v_lshlrev_b32_e32 v4, 16, v4
	v_mov_b32_e32 v62, v145
	v_lshlrev_b32_e32 v2, 16, v2
	v_add_f32_e32 v3, v25, v5
	v_mul_f32_e32 v41, v41, v4
	v_mul_f32_e32 v25, v3, v2
	v_mov_b64_e32 v[2:3], v[184:185]
	v_mov_b64_e32 v[4:5], v[186:187]
	v_mov_b32_e32 v63, v1
	v_lshlrev_b32_e32 v62, 16, v62
	v_add_f32_e32 v42, v42, v2
	v_add_f32_e32 v2, v26, v2
	v_mul_f32_e32 v26, v2, v62
	v_or_b32_e32 v2, 49, v86
	v_mul_lo_u32 v62, v2, s80
	v_lshl_add_u64 v[62:63], s[4:5], 0, v[62:63]
	v_lshl_add_u64 v[62:63], v[62:63], 0, s[0:1]
	v_lshl_add_u64 v[62:63], v[62:63], 0, v[10:11]
	v_mov_b32_e32 v2, v146
	v_add_f32_e32 v43, v43, v3
	v_add_f32_e32 v3, v27, v3
	v_add_f32_e32 v44, v44, v4
	v_add_f32_e32 v45, v45, v5
	v_mul_f32_e32 v42, v42, v64
	v_lshlrev_b32_e32 v2, 16, v2
	v_mul_f32_e32 v43, v43, v2
	v_mov_b32_e32 v2, v147
	v_lshlrev_b32_e32 v2, 16, v2
	v_mul_f32_e32 v27, v3, v2
	v_or_b32_e32 v2, 50, v86
	v_mul_lo_u32 v2, v2, s80
	v_mov_b32_e32 v3, v1
	v_lshl_add_u64 v[2:3], s[4:5], 0, v[2:3]
	v_lshl_add_u64 v[2:3], v[2:3], 0, s[0:1]
	v_lshl_add_u64 v[2:3], v[2:3], 0, v[10:11]
	v_mov_b32_e32 v62, v148
	v_lshlrev_b32_e32 v62, 16, v62
	v_mov_b32_e32 v2, v149
	v_add_f32_e32 v3, v28, v4
	v_mul_f32_e32 v44, v44, v62
	v_lshlrev_b32_e32 v2, 16, v2
	v_mul_f32_e32 v28, v3, v2
	v_or_b32_e32 v2, 51, v86
	v_mul_lo_u32 v2, v2, s80
	v_mov_b32_e32 v3, v1
	v_lshl_add_u64 v[2:3], s[4:5], 0, v[2:3]
	v_lshl_add_u64 v[2:3], v[2:3], 0, s[0:1]
	v_lshl_add_u64 v[2:3], v[2:3], 0, v[10:11]
	v_mov_b32_e32 v4, v150
	v_lshlrev_b32_e32 v4, 16, v4
	v_mov_b32_e32 v2, v151
	v_add_f32_e32 v3, v29, v5
; __device__ __forceinline__ float bf2f(unsigned short h) { return __uint_as_float(((unsigned)h) << 16); }
; __device__ __forceinline__ int crow(int r, int hi) { return (r & 3) + 8 * (r >> 2) + 4 * hi; }
; __device__ __forceinline__ unsigned cvtpk_s(float lo, float hi) { typedef __bf16 bf16x2_t __attribute__((ext_vector_type(2))); f32x2 v = {lo, hi}; bf16x2_t b = __builtin_convertvector(v, bf16x2_t); return __builtin_bit_cast(unsigned, b); }
; __device__ __forceinline__ void store_tile(const f32x16* o, const float* rli, bf16_t* stg, bf16_t* Ow, int pitch, float* ss, int lane, int r32, int hi) {
; #pragma unroll
;     for (int r = 0; r < 16; ++r) { const int orow = crow(r, hi);
; #pragma unroll
;         for (int d0 = 0; d0 < 2; ++d0) stg[orow * 64 + d0 * 32 + r32] = (bf16_t)(cvtpk_s(o[d0][r] * rli[r], 0.f) & 0xffffu); }
;     asm volatile("s_waitcnt lgkmcnt(0)" ::: "memory");
; #pragma unroll
;     for (int i = 0; i < 4; ++i) { const int row = i * 8 + (lane >> 3), ch = lane & 7; const u32x4 v = *(const u32x4*)(stg + row * 64 + ch * 8);
;         { const bf16_t* gp_ = Ow + (long)row * pitch + ch * 8; asm volatile("global_store_dwordx4 %0, %1, off sc0 sc1\n\ts_nop 1" :: "v"(gp_), "v"(v) : "memory"); }
;         float s = 0.f;
; #pragma unroll
;         for (int j = 0; j < 4; ++j) { const float a = __uint_as_float(v[j] << 16), b = __uint_as_float(v[j] & 0xffff0000u); s += a * a + b * b; }
;         s += __shfl_xor(s, 1); s += __shfl_xor(s, 2); s += __shfl_xor(s, 4);
;         if (ch == 0) atomicAdd(ss + (long)row * 4, s); }
;     asm volatile("s_waitcnt lgkmcnt(0)" ::: "memory");
; __device__ __forceinline__ void sg_unit(const Params& P, int l, int chunk, char* shm, float* ssb) {
;     ...
;     for (int pt = 0; pt < 2; ++pt) {
;         f32x16 o[2];
; #pragma unroll
;         for (int r = 0; r < 16; ++r) { const int p = 64 * ph + 32 * pt + at::crow(r, hi); const float bp = bs[p];
; #pragma unroll
;             for (int ct = 0; ct < 2; ++ct) { const float uu = bf2f(qkv[(size_t)(R0 + p) * DIN + C_U + 64 * g + 32 * ct + r32]); o[ct][r] = uu * (acc[pt][ct][r] + bp); } }
;         const int prow = R0 + 64 * ph + 32 * pt;
;         at::store_tile(o, ones, (bf16_t*)(shm + SG_STAGE) + wid * 2048, omix + (size_t)prow * DM + 384 + 64 * g, DM, ssb + (size_t)prow * 4 + 1, lane, r32, hi);
	v_mul_f32_e32 v45, v45, v4
	v_lshlrev_b32_e32 v2, 16, v2
	v_mul_f32_e32 v29, v3, v2
	v_mov_b64_e32 v[2:3], v[188:189]
	v_mov_b64_e32 v[4:5], v[190:191]
	v_or_b32_e32 v56, 56, v86
	v_mul_lo_u32 v56, v56, s80
	v_mov_b32_e32 v57, v1
	v_lshl_add_u64 v[56:57], s[4:5], 0, v[56:57]
	v_lshl_add_u64 v[56:57], v[56:57], 0, s[0:1]
	v_lshl_add_u64 v[56:57], v[56:57], 0, v[10:11]
	v_mov_b32_e32 v62, v152
	v_add_f32_e32 v46, v46, v2
	v_mov_b32_e32 v56, v153
	v_add_f32_e32 v2, v30, v2
	v_or_b32_e32 v30, 57, v86
	v_mov_b32_e32 v57, v1
	v_add_f32_e32 v47, v47, v3
	v_add_f32_e32 v3, v31, v3
	v_or_b32_e32 v31, 58, v86
	v_lshlrev_b32_e32 v62, 16, v62
	v_mul_f32_e32 v46, v46, v62
	v_lshlrev_b32_e32 v56, 16, v56
	v_mul_f32_e32 v2, v2, v56
	v_mul_lo_u32 v56, v30, s80
	v_lshl_add_u64 v[56:57], s[4:5], 0, v[56:57]
	v_lshl_add_u64 v[56:57], v[56:57], 0, s[0:1]
	v_lshl_add_u64 v[56:57], v[56:57], 0, v[10:11]
	v_mov_b32_e32 v30, v154
	v_lshlrev_b32_e32 v30, 16, v30
	v_mul_f32_e32 v30, v47, v30
	v_mov_b32_e32 v47, v155
	v_mul_lo_u32 v56, v31, s80
	v_mov_b32_e32 v57, v1
	v_lshl_add_u64 v[56:57], s[4:5], 0, v[56:57]
	v_lshl_add_u64 v[56:57], v[56:57], 0, s[0:1]
	v_lshl_add_u64 v[56:57], v[56:57], 0, v[10:11]
	v_mov_b32_e32 v31, v156
	v_lshlrev_b32_e32 v47, 16, v47
	v_mul_f32_e32 v3, v3, v47
	v_add_f32_e32 v47, v48, v4
	v_add_f32_e32 v4, v32, v4
	v_or_b32_e32 v32, 59, v86
	v_lshlrev_b32_e32 v31, 16, v31
	v_mul_f32_e32 v31, v47, v31
	v_mov_b32_e32 v47, v157
	v_mul_lo_u32 v56, v32, s80
	v_mov_b32_e32 v57, v1
	v_lshl_add_u64 v[56:57], s[4:5], 0, v[56:57]
	v_lshl_add_u64 v[56:57], v[56:57], 0, s[0:1]
	v_lshl_add_u64 v[10:11], v[56:57], 0, v[10:11]
	v_mov_b32_e32 v32, v158
	s_lshl_b64 s[4:5], s[86:87], 11
	v_mov_b32_e32 v10, v159
	s_add_u32 s2, s76, s4
	s_addc_u32 s5, s77, s5
	s_add_u32 s4, s2, s0
	s_addc_u32 s5, s5, s1
	s_lshl_b64 s[0:1], s[86:87], 4
	s_add_u32 s0, s10, s0
	v_cvt_pk_bf16_f32 v2, v2, s0
	ds_write_b16 v85, v2 offset:3136
	v_cvt_pk_bf16_f32 v2, v30, s0
	ds_write_b16 v85, v2 offset:3200
	v_cvt_pk_bf16_f32 v2, v3, s0
	ds_write_b16 v85, v2 offset:3264
	v_cvt_pk_bf16_f32 v2, v31, s0
	ds_write_b16 v85, v2 offset:3328
	v_mov_b32_e32 v3, v1
	s_addc_u32 s1, s11, s1
	v_lshlrev_b32_e32 v47, 16, v47
	v_mul_f32_e32 v4, v4, v47
	v_add_f32_e32 v47, v49, v5
	v_add_f32_e32 v5, v33, v5
	v_cvt_pk_bf16_f32 v2, v4, s0
	ds_write_b16 v85, v2 offset:3392
	v_lshlrev_b32_e32 v32, 16, v32
	v_mul_f32_e32 v32, v47, v32
	v_lshlrev_b32_e32 v10, 16, v10
	v_mul_f32_e32 v5, v5, v10
	v_cvt_pk_bf16_f32 v10, v34, s0
	ds_write_b16 v85, v10
	v_cvt_pk_bf16_f32 v10, v18, s0
	ds_write_b16 v85, v10 offset:64
	v_cvt_pk_bf16_f32 v10, v35, s0
	ds_write_b16 v85, v10 offset:128
	v_cvt_pk_bf16_f32 v10, v19, s0
	ds_write_b16 v85, v10 offset:192
	v_cvt_pk_bf16_f32 v10, v36, s0
	ds_write_b16 v85, v10 offset:256
	v_cvt_pk_bf16_f32 v10, v20, s0
	ds_write_b16 v85, v10 offset:320
	v_cvt_pk_bf16_f32 v10, v37, s0
	ds_write_b16 v85, v10 offset:384
	v_cvt_pk_bf16_f32 v10, v21, s0
	ds_write_b16 v85, v10 offset:448
	v_cvt_pk_bf16_f32 v10, v38, s0
	ds_write_b16 v85, v10 offset:1024
	v_cvt_pk_bf16_f32 v10, v22, s0
	ds_write_b16 v85, v10 offset:1088
	v_cvt_pk_bf16_f32 v10, v39, s0
	ds_write_b16 v85, v10 offset:1152
	v_cvt_pk_bf16_f32 v10, v23, s0
	ds_write_b16 v85, v10 offset:1216
	v_cvt_pk_bf16_f32 v10, v40, s0
	ds_write_b16 v85, v10 offset:1280
	v_cvt_pk_bf16_f32 v10, v24, s0
	ds_write_b16 v85, v10 offset:1344
	v_cvt_pk_bf16_f32 v10, v41, s0
	ds_write_b16 v85, v10 offset:1408
	v_cvt_pk_bf16_f32 v10, v25, s0
	ds_write_b16 v85, v10 offset:1472
	v_cvt_pk_bf16_f32 v10, v42, s0
	ds_write_b16 v85, v10 offset:2048
	v_cvt_pk_bf16_f32 v10, v26, s0
	ds_write_b16 v85, v10 offset:2112
	v_cvt_pk_bf16_f32 v10, v43, s0
	ds_write_b16 v85, v10 offset:2176
	v_cvt_pk_bf16_f32 v10, v27, s0
	ds_write_b16 v85, v10 offset:2240
	v_cvt_pk_bf16_f32 v10, v44, s0
	ds_write_b16 v85, v10 offset:2304
	v_cvt_pk_bf16_f32 v10, v28, s0
	ds_write_b16 v85, v10 offset:2368
	v_cvt_pk_bf16_f32 v10, v45, s0
	ds_write_b16 v85, v10 offset:2432
	v_cvt_pk_bf16_f32 v10, v29, s0
	v_cvt_pk_bf16_f32 v2, v32, s0
	ds_write_b16 v85, v10 offset:2496
	v_cvt_pk_bf16_f32 v10, v46, s0
	ds_write_b16 v85, v2 offset:3456
	v_cvt_pk_bf16_f32 v2, v5, s0
	ds_write_b16 v85, v10 offset:3072
	ds_write_b16 v85, v2 offset:3520
	s_waitcnt lgkmcnt(0)
	ds_read_b128 v[18:21], v84
	v_lshlrev_b32_e32 v2, 1, v61
	v_lshl_add_u64 v[2:3], s[4:5], 0, v[2:3]
	s_mov_b64 s[4:5], 0x12e40300
	v_lshl_add_u64 v[2:3], v[2:3], 0, s[4:5]
	v_lshl_add_u64 v[4:5], v[2:3], 0, v[8:9]
	s_waitcnt lgkmcnt(0)
	global_store_dwordx4 v[4:5], v[18:21], off sc0 sc1
	s_nop 1
	v_and_b32_e32 v5, 0xffff0000, v18
	v_lshlrev_b32_e32 v4, 16, v18
	v_mul_f32_e32 v5, v5, v5
	v_and_b32_e32 v8, 0xffff0000, v19
	v_fmac_f32_e32 v5, v4, v4
	v_lshlrev_b32_e32 v4, 16, v19
	v_mul_f32_e32 v8, v8, v8
	v_fmac_f32_e32 v8, v4, v4
	v_add_f32_e32 v4, v5, v8
	v_and_b32_e32 v8, 0xffff0000, v20
	v_lshlrev_b32_e32 v5, 16, v20
	v_mul_f32_e32 v8, v8, v8
	v_fmac_f32_e32 v8, v5, v5
	v_add_f32_e32 v4, v8, v4
	v_and_b32_e32 v8, 0xffff0000, v21
	v_lshlrev_b32_e32 v5, 16, v21
	v_mul_f32_e32 v8, v8, v8
	v_fmac_f32_e32 v8, v5, v5
	v_add_f32_e32 v4, v8, v4
	ds_bpermute_b32 v5, v17, v4
	s_waitcnt lgkmcnt(0)
	v_add_f32_e32 v4, v4, v5
	ds_bpermute_b32 v5, v83, v4
	s_waitcnt lgkmcnt(0)
	v_add_f32_e32 v4, v4, v5
	ds_bpermute_b32 v5, v82, v4
	s_and_saveexec_b64 s[4:5], vcc
	s_cbranch_execz .LBB0_570
	v_lshl_add_u64 v[6:7], s[0:1], 0, v[6:7]
	s_waitcnt lgkmcnt(0)
	v_add_f32_e32 v4, v4, v5
	flat_atomic_add_f32 v[6:7], v4 offset:4
